# GEMM K loops: the compiler's duplicate s_waitcnt lgkmcnt(0) between each pre-MFMA barrier and the first MFMA removed (the counted wait before the barrier already covers it)
# speedup vs baseline: 1.0022x; 1.0022x over previous
; #define PG8_STAGE(bufoff, gbase, voff) do { _Pragma("unroll") for (int _i = 0; _i < 2; ++_i) \
;         __builtin_amdgcn_global_load_lds((const unsigned*)((const char*)(gbase) + (voff)[_i]), (PG8_LAS unsigned*)(lds + (bufoff) + ldsw + _i * 8192), 16, 0, 0); } while (0)
; #define PG8_LDA(dst, b, h) do { _Pragma("unroll") for (int m = 0; m < 4; ++m) _Pragma("unroll") for (int k = 0; k < 2; ++k) dst[m][k] = *(const PG8_LAS bf16x8*)(lds + PG8_SA(b, h) + aoff + m * 2048 + k * 1024); } while (0)
; #define PG8_LDB(dst, b, h) do { _Pragma("unroll") for (int n = 0; n < 2; ++n) _Pragma("unroll") for (int k = 0; k < 2; ++k) dst[n][k] = *(const PG8_LAS bf16x8*)(lds + PG8_SB(b, h) + boff + n * 2048 + k * 1024); } while (0)
; #define PG8_MMA(ai, bj, At, Bt) do { __builtin_amdgcn_s_setprio(1); _Pragma("unroll") for (int m = 0; m < 4; ++m) _Pragma("unroll") for (int n = 0; n < 2; ++n) _Pragma("unroll") for (int k = 0; k < 2; ++k) \
;         acc[ai][bj][m][n] = __builtin_amdgcn_mfma_f32_16x16x32_bf16(Bt[n][k], At[m][k], acc[ai][bj][m][n], 0, 0, 0); __builtin_amdgcn_s_setprio(0); } while (0)
; #define PG8_WAIT_V(n) asm volatile("s_waitcnt vmcnt(" #n ")" ::: "memory")
; #define PG8_WAIT_L(n) asm volatile("s_waitcnt lgkmcnt(" #n ")" ::: "memory")
; #define PG8_BAR __builtin_amdgcn_s_barrier()
; #define PG8_SCHED __builtin_amdgcn_sched_barrier(0)
; template <class Epi, class Sched, bool ALIGN_EPI = false, bool SP2 = false>
; __device__ __forceinline__ void gemm_phase(PG8_LAS unsigned char* lds, const Gemm g, const Sched S, const Epi E) {
;     ...
;             const bool last = (t == nt - 2);
;             const char* a1 = cA + (size_t)(t + 1) * kstep;
;             const char* a2 = last ? nA : cA + (size_t)(t + 2) * kstep; const char* b2 = last ? nB : cB + (size_t)(t + 2) * kstep;
;             const char* a3 = a2 + kstep; const char* b3 = b2 + kstep;
;             if (last && has_next) S.a_ready(nxt);
;             if constexpr (SP2) {
;             PG8_LDB(B0, 0, 0); PG8_LDB(B1, 0, 1); PG8_SCHED; PG8_LDA(At, 0, 0); PG8_STAGE(PG8_SA(1, 1), a1 + hstep, voffA);
;             PG8_WAIT_V(8); PG8_WAIT_L(0); PG8_BAR; PG8_MMA(0, 0, At, B0); PG8_MMA(0, 1, At, B1); PG8_BAR; PG8_SCHED;
;             PG8_LDA(At, 0, 1); PG8_STAGE(PG8_SB(0, 0), b2, voffB); PG8_STAGE(PG8_SB(0, 1), b2 + hstep, voffB); PG8_STAGE(PG8_SA(0, 0), a2, voffA);
.LBB0_180:
	v_add_u32_e32 v140, 0x10000, v143
	ds_read_b128 v[154:157], v140
	ds_read_b128 v[158:161], v140 offset:1024
	ds_read_b128 v[162:165], v140 offset:2048
	ds_read_b128 v[166:169], v140 offset:3072
	v_add_u32_e32 v140, 0x14000, v143
	ds_read_b128 v[170:173], v140
	ds_read_b128 v[174:177], v140 offset:1024
	ds_read_b128 v[182:185], v140 offset:2048
	ds_read_b128 v[198:201], v140 offset:3072
	s_add_i32 s20, s18, 2
	s_add_u32 s21, s16, 0x80
	s_addc_u32 s19, s17, 0
	s_add_i32 s25, 0, 0x10000
	s_cmp_eq_u32 s75, s18
	s_cselect_b32 s19, s1, s19
	s_cselect_b32 s18, s0, s21
	s_cselect_b32 s23, s59, s15
	s_cselect_b32 s22, s58, s14
	s_add_i32 s21, 0, 0x14000
	v_lshl_add_u64 v[140:141], s[16:17], 0, v[136:137]
	s_add_i32 m0, s68, 0xc000
	ds_read_b128 v[202:205], v146
	ds_read_b128 v[206:209], v146 offset:1024
	ds_read_b128 v[210:213], v146 offset:2048
	ds_read_b128 v[214:217], v146 offset:3072
	ds_read_b128 v[218:221], v146 offset:4096
	ds_read_b128 v[222:225], v146 offset:5120
	ds_read_b128 v[226:229], v146 offset:6144
	ds_read_b128 v[230:233], v146 offset:7168
	global_load_lds_dwordx4 v[140:141], off
	v_lshl_add_u64 v[140:141], s[16:17], 0, v[138:139]
	s_add_i32 m0, s68, 0xe000
	s_nop 0
	global_load_lds_dwordx4 v[140:141], off
	s_waitcnt vmcnt(8)
	s_waitcnt lgkmcnt(0)
	s_barrier
	s_setprio 1
	v_mfma_f32_16x16x32_bf16 v[126:129], v[154:157], v[202:205], v[126:129]
	v_mfma_f32_16x16x32_bf16 v[118:121], v[162:165], v[202:205], v[118:121]
	v_mfma_f32_16x16x32_bf16 v[110:113], v[154:157], v[210:213], v[110:113]
	v_mfma_f32_16x16x32_bf16 v[102:105], v[162:165], v[210:213], v[102:105]
	v_mfma_f32_16x16x32_bf16 v[94:97], v[154:157], v[218:221], v[94:97]
	v_mfma_f32_16x16x32_bf16 v[86:89], v[162:165], v[218:221], v[86:89]
	v_mfma_f32_16x16x32_bf16 v[78:81], v[154:157], v[226:229], v[78:81]
	v_mfma_f32_16x16x32_bf16 v[70:73], v[162:165], v[226:229], v[70:73]
	v_mfma_f32_16x16x32_bf16 v[126:129], v[158:161], v[206:209], v[126:129]
	v_mfma_f32_16x16x32_bf16 v[118:121], v[166:169], v[206:209], v[118:121]
	v_mfma_f32_16x16x32_bf16 v[110:113], v[158:161], v[214:217], v[110:113]
	v_mfma_f32_16x16x32_bf16 v[102:105], v[166:169], v[214:217], v[102:105]
	v_mfma_f32_16x16x32_bf16 v[94:97], v[158:161], v[222:225], v[94:97]
	v_mfma_f32_16x16x32_bf16 v[86:89], v[166:169], v[222:225], v[86:89]
	v_mfma_f32_16x16x32_bf16 v[78:81], v[158:161], v[230:233], v[78:81]
	v_mfma_f32_16x16x32_bf16 v[70:73], v[166:169], v[230:233], v[70:73]
	s_setprio 0
	s_setprio 1
	v_mfma_f32_16x16x32_bf16 v[122:125], v[170:173], v[202:205], v[122:125]
	v_mfma_f32_16x16x32_bf16 v[114:117], v[182:185], v[202:205], v[114:117]
	v_mfma_f32_16x16x32_bf16 v[106:109], v[170:173], v[210:213], v[106:109]
	v_mfma_f32_16x16x32_bf16 v[98:101], v[182:185], v[210:213], v[98:101]
	v_mfma_f32_16x16x32_bf16 v[90:93], v[170:173], v[218:221], v[90:93]
	v_mfma_f32_16x16x32_bf16 v[82:85], v[182:185], v[218:221], v[82:85]
	v_mfma_f32_16x16x32_bf16 v[74:77], v[170:173], v[226:229], v[74:77]
	v_mfma_f32_16x16x32_bf16 v[66:69], v[182:185], v[226:229], v[66:69]
	v_mfma_f32_16x16x32_bf16 v[122:125], v[174:177], v[206:209], v[122:125]
	v_mfma_f32_16x16x32_bf16 v[114:117], v[198:201], v[206:209], v[114:117]
	v_mfma_f32_16x16x32_bf16 v[106:109], v[174:177], v[214:217], v[106:109]
	v_mfma_f32_16x16x32_bf16 v[98:101], v[198:201], v[214:217], v[98:101]
	v_mfma_f32_16x16x32_bf16 v[90:93], v[174:177], v[222:225], v[90:93]
	v_mfma_f32_16x16x32_bf16 v[82:85], v[198:201], v[222:225], v[82:85]
	v_mfma_f32_16x16x32_bf16 v[74:77], v[174:177], v[230:233], v[74:77]
	v_mfma_f32_16x16x32_bf16 v[66:69], v[198:201], v[230:233], v[66:69]
	s_setprio 0
	s_barrier
	s_add_i32 s25, s25, s61
	v_lshl_add_u64 v[140:141], s[22:23], 0, v[0:1]
	s_mov_b32 m0, s25
	ds_read_b128 v[202:205], v146 offset:16384
	ds_read_b128 v[206:209], v146 offset:17408
	ds_read_b128 v[210:213], v146 offset:18432
	ds_read_b128 v[214:217], v146 offset:19456
	ds_read_b128 v[218:221], v146 offset:20480
	ds_read_b128 v[222:225], v146 offset:21504
	ds_read_b128 v[226:229], v146 offset:22528
	ds_read_b128 v[230:233], v146 offset:23552
	global_load_lds_dwordx4 v[140:141], off
	s_add_i32 m0, s25, 0x2000
	v_lshl_add_u64 v[234:235], s[22:23], 0, v[130:131]
	s_add_u32 s22, s22, s28
	s_addc_u32 s23, s23, 0
	s_add_i32 s21, s21, s61
	global_load_lds_dwordx4 v[234:235], off
	v_lshl_add_u64 v[236:237], s[22:23], 0, v[0:1]
	s_mov_b32 m0, s21
	v_lshl_add_u64 v[238:239], s[22:23], 0, v[130:131]
	global_load_lds_dwordx4 v[236:237], off
	s_add_i32 m0, s21, 0x2000
	v_lshl_add_u64 v[240:241], s[18:19], 0, v[134:135]
	global_load_lds_dwordx4 v[238:239], off
	s_mov_b32 m0, s68
	v_lshl_add_u64 v[242:243], s[18:19], 0, v[132:133]
	global_load_lds_dwordx4 v[240:241], off
	s_mov_b32 m0, s69
	s_nop 0
	global_load_lds_dwordx4 v[242:243], off
	s_waitcnt vmcnt(8)
	s_waitcnt lgkmcnt(0)
	s_barrier
; #define PG8_STAGE(bufoff, gbase, voff) do { _Pragma("unroll") for (int _i = 0; _i < 2; ++_i) \
;         __builtin_amdgcn_global_load_lds((const unsigned*)((const char*)(gbase) + (voff)[_i]), (PG8_LAS unsigned*)(lds + (bufoff) + ldsw + _i * 8192), 16, 0, 0); } while (0)
; #define PG8_LDA(dst, b, h) do { _Pragma("unroll") for (int m = 0; m < 4; ++m) _Pragma("unroll") for (int k = 0; k < 2; ++k) dst[m][k] = *(const PG8_LAS bf16x8*)(lds + PG8_SA(b, h) + aoff + m * 2048 + k * 1024); } while (0)
; #define PG8_LDB(dst, b, h) do { _Pragma("unroll") for (int n = 0; n < 2; ++n) _Pragma("unroll") for (int k = 0; k < 2; ++k) dst[n][k] = *(const PG8_LAS bf16x8*)(lds + PG8_SB(b, h) + boff + n * 2048 + k * 1024); } while (0)
; #define PG8_MMA(ai, bj, At, Bt) do { __builtin_amdgcn_s_setprio(1); _Pragma("unroll") for (int m = 0; m < 4; ++m) _Pragma("unroll") for (int n = 0; n < 2; ++n) _Pragma("unroll") for (int k = 0; k < 2; ++k) \
;         acc[ai][bj][m][n] = __builtin_amdgcn_mfma_f32_16x16x32_bf16(Bt[n][k], At[m][k], acc[ai][bj][m][n], 0, 0, 0); __builtin_amdgcn_s_setprio(0); } while (0)
; #define PG8_WAIT_V(n) asm volatile("s_waitcnt vmcnt(" #n ")" ::: "memory")
; #define PG8_WAIT_L(n) asm volatile("s_waitcnt lgkmcnt(" #n ")" ::: "memory")
; #define PG8_BAR __builtin_amdgcn_s_barrier()
; #define PG8_SCHED __builtin_amdgcn_sched_barrier(0)
; template <class Epi, class Sched, bool ALIGN_EPI = false, bool SP2 = false>
; __device__ __forceinline__ void gemm_phase(PG8_LAS unsigned char* lds, const Gemm g, const Sched S, const Epi E) {
;     ...
;             PG8_WAIT_V(8); PG8_WAIT_L(0); PG8_BAR; PG8_MMA(1, 0, At, B0); PG8_MMA(1, 1, At, B1); PG8_BAR; PG8_SCHED;
;             PG8_LDB(B0, 1, 0); PG8_LDB(B1, 1, 1); PG8_SCHED; PG8_LDA(At, 1, 0); PG8_STAGE(PG8_SA(0, 1), a2 + hstep, voffA);
;             PG8_WAIT_V(8); PG8_WAIT_L(0); PG8_BAR; PG8_MMA(0, 0, At, B0); PG8_MMA(0, 1, At, B1); PG8_BAR; PG8_SCHED;
	s_setprio 1
	v_mfma_f32_16x16x32_bf16 v[62:65], v[154:157], v[202:205], v[62:65]
	v_mfma_f32_16x16x32_bf16 v[54:57], v[162:165], v[202:205], v[54:57]
	v_mfma_f32_16x16x32_bf16 v[46:49], v[154:157], v[210:213], v[46:49]
	v_mfma_f32_16x16x32_bf16 v[38:41], v[162:165], v[210:213], v[38:41]
	v_mfma_f32_16x16x32_bf16 v[30:33], v[154:157], v[218:221], v[30:33]
	v_mfma_f32_16x16x32_bf16 v[22:25], v[162:165], v[218:221], v[22:25]
	v_mfma_f32_16x16x32_bf16 v[14:17], v[154:157], v[226:229], v[14:17]
	v_mfma_f32_16x16x32_bf16 v[6:9], v[162:165], v[226:229], v[6:9]
	v_mfma_f32_16x16x32_bf16 v[62:65], v[158:161], v[206:209], v[62:65]
	v_mfma_f32_16x16x32_bf16 v[54:57], v[166:169], v[206:209], v[54:57]
	v_mfma_f32_16x16x32_bf16 v[46:49], v[158:161], v[214:217], v[46:49]
	v_mfma_f32_16x16x32_bf16 v[38:41], v[166:169], v[214:217], v[38:41]
	v_mfma_f32_16x16x32_bf16 v[30:33], v[158:161], v[222:225], v[30:33]
	v_mfma_f32_16x16x32_bf16 v[22:25], v[166:169], v[222:225], v[22:25]
	v_mfma_f32_16x16x32_bf16 v[14:17], v[158:161], v[230:233], v[14:17]
	v_mfma_f32_16x16x32_bf16 v[6:9], v[166:169], v[230:233], v[6:9]
	s_setprio 0
	s_setprio 1
	v_mfma_f32_16x16x32_bf16 v[58:61], v[170:173], v[202:205], v[58:61]
	v_mfma_f32_16x16x32_bf16 v[50:53], v[182:185], v[202:205], v[50:53]
	v_mfma_f32_16x16x32_bf16 v[42:45], v[170:173], v[210:213], v[42:45]
	v_mfma_f32_16x16x32_bf16 v[34:37], v[182:185], v[210:213], v[34:37]
	v_mfma_f32_16x16x32_bf16 v[26:29], v[170:173], v[218:221], v[26:29]
	v_mfma_f32_16x16x32_bf16 v[18:21], v[182:185], v[218:221], v[18:21]
	v_mfma_f32_16x16x32_bf16 v[10:13], v[170:173], v[226:229], v[10:13]
	v_mfma_f32_16x16x32_bf16 v[2:5], v[182:185], v[226:229], v[2:5]
	v_mfma_f32_16x16x32_bf16 v[58:61], v[174:177], v[206:209], v[58:61]
	v_mfma_f32_16x16x32_bf16 v[50:53], v[198:201], v[206:209], v[50:53]
	v_mfma_f32_16x16x32_bf16 v[42:45], v[174:177], v[214:217], v[42:45]
	v_mfma_f32_16x16x32_bf16 v[34:37], v[198:201], v[214:217], v[34:37]
	v_mfma_f32_16x16x32_bf16 v[26:29], v[174:177], v[222:225], v[26:29]
	v_mfma_f32_16x16x32_bf16 v[18:21], v[198:201], v[222:225], v[18:21]
	v_mfma_f32_16x16x32_bf16 v[10:13], v[174:177], v[230:233], v[10:13]
	v_mfma_f32_16x16x32_bf16 v[2:5], v[198:201], v[230:233], v[2:5]
	s_setprio 0
	s_barrier
	v_add_u32_e32 v166, 0x18000, v143
	v_add_u32_e32 v186, 0x1c000, v143
	ds_read_b128 v[154:157], v166
	ds_read_b128 v[158:161], v166 offset:1024
	ds_read_b128 v[162:165], v166 offset:2048
	ds_read_b128 v[166:169], v166 offset:3072
	ds_read_b128 v[170:173], v186
	ds_read_b128 v[174:177], v186 offset:1024
	ds_read_b128 v[182:185], v186 offset:2048
	ds_read_b128 v[198:201], v186 offset:3072
	s_add_i32 s21, 0, 0x18000
	s_add_i32 s22, 0, 0x1c000
	s_add_u32 s18, s18, s28
	s_addc_u32 s19, s19, 0
	s_mov_b32 m0, s70
	v_lshl_add_u64 v[244:245], s[18:19], 0, v[134:135]
	ds_read_b128 v[202:205], v146 offset:32768
	ds_read_b128 v[206:209], v146 offset:33792
	ds_read_b128 v[210:213], v146 offset:34816
	ds_read_b128 v[214:217], v146 offset:35840
	ds_read_b128 v[218:221], v146 offset:36864
	ds_read_b128 v[222:225], v146 offset:37888
	ds_read_b128 v[226:229], v146 offset:38912
	ds_read_b128 v[230:233], v146 offset:39936
	global_load_lds_dwordx4 v[244:245], off
	v_lshl_add_u64 v[244:245], s[18:19], 0, v[132:133]
	s_mov_b32 m0, s71
	s_nop 0
	global_load_lds_dwordx4 v[244:245], off
	s_waitcnt vmcnt(8)
	s_waitcnt lgkmcnt(0)
	s_barrier
	s_setprio 1
	v_mfma_f32_16x16x32_bf16 v[126:129], v[154:157], v[202:205], v[126:129]
	v_mfma_f32_16x16x32_bf16 v[118:121], v[162:165], v[202:205], v[118:121]
	v_mfma_f32_16x16x32_bf16 v[110:113], v[154:157], v[210:213], v[110:113]
	v_mfma_f32_16x16x32_bf16 v[102:105], v[162:165], v[210:213], v[102:105]
	v_mfma_f32_16x16x32_bf16 v[94:97], v[154:157], v[218:221], v[94:97]
	v_mfma_f32_16x16x32_bf16 v[86:89], v[162:165], v[218:221], v[86:89]
	v_mfma_f32_16x16x32_bf16 v[78:81], v[154:157], v[226:229], v[78:81]
	v_mfma_f32_16x16x32_bf16 v[70:73], v[162:165], v[226:229], v[70:73]
	v_mfma_f32_16x16x32_bf16 v[126:129], v[158:161], v[206:209], v[126:129]
	v_mfma_f32_16x16x32_bf16 v[118:121], v[166:169], v[206:209], v[118:121]
	v_mfma_f32_16x16x32_bf16 v[110:113], v[158:161], v[214:217], v[110:113]
	v_mfma_f32_16x16x32_bf16 v[102:105], v[166:169], v[214:217], v[102:105]
	v_mfma_f32_16x16x32_bf16 v[94:97], v[158:161], v[222:225], v[94:97]
	v_mfma_f32_16x16x32_bf16 v[86:89], v[166:169], v[222:225], v[86:89]
	v_mfma_f32_16x16x32_bf16 v[78:81], v[158:161], v[230:233], v[78:81]
	v_mfma_f32_16x16x32_bf16 v[70:73], v[166:169], v[230:233], v[70:73]
	s_setprio 0
	s_setprio 1
	v_mfma_f32_16x16x32_bf16 v[122:125], v[170:173], v[202:205], v[122:125]
	v_mfma_f32_16x16x32_bf16 v[114:117], v[182:185], v[202:205], v[114:117]
	v_mfma_f32_16x16x32_bf16 v[106:109], v[170:173], v[210:213], v[106:109]
	v_mfma_f32_16x16x32_bf16 v[98:101], v[182:185], v[210:213], v[98:101]
	v_mfma_f32_16x16x32_bf16 v[90:93], v[170:173], v[218:221], v[90:93]
	v_mfma_f32_16x16x32_bf16 v[82:85], v[182:185], v[218:221], v[82:85]
	v_mfma_f32_16x16x32_bf16 v[74:77], v[170:173], v[226:229], v[74:77]
	v_mfma_f32_16x16x32_bf16 v[66:69], v[182:185], v[226:229], v[66:69]
	v_mfma_f32_16x16x32_bf16 v[122:125], v[174:177], v[206:209], v[122:125]
	v_mfma_f32_16x16x32_bf16 v[114:117], v[198:201], v[206:209], v[114:117]
	v_mfma_f32_16x16x32_bf16 v[106:109], v[174:177], v[214:217], v[106:109]
	v_mfma_f32_16x16x32_bf16 v[98:101], v[198:201], v[214:217], v[98:101]
	v_mfma_f32_16x16x32_bf16 v[90:93], v[174:177], v[222:225], v[90:93]
	v_mfma_f32_16x16x32_bf16 v[82:85], v[198:201], v[222:225], v[82:85]
	v_mfma_f32_16x16x32_bf16 v[74:77], v[174:177], v[230:233], v[74:77]
	v_mfma_f32_16x16x32_bf16 v[66:69], v[198:201], v[230:233], v[66:69]
	s_setprio 0
	s_barrier
; #define PG8_STAGE(bufoff, gbase, voff) do { _Pragma("unroll") for (int _i = 0; _i < 2; ++_i) \
;         __builtin_amdgcn_global_load_lds((const unsigned*)((const char*)(gbase) + (voff)[_i]), (PG8_LAS unsigned*)(lds + (bufoff) + ldsw + _i * 8192), 16, 0, 0); } while (0)
; #define PG8_LDA(dst, b, h) do { _Pragma("unroll") for (int m = 0; m < 4; ++m) _Pragma("unroll") for (int k = 0; k < 2; ++k) dst[m][k] = *(const PG8_LAS bf16x8*)(lds + PG8_SA(b, h) + aoff + m * 2048 + k * 1024); } while (0)
; #define PG8_MMA(ai, bj, At, Bt) do { __builtin_amdgcn_s_setprio(1); _Pragma("unroll") for (int m = 0; m < 4; ++m) _Pragma("unroll") for (int n = 0; n < 2; ++n) _Pragma("unroll") for (int k = 0; k < 2; ++k) \
;         acc[ai][bj][m][n] = __builtin_amdgcn_mfma_f32_16x16x32_bf16(Bt[n][k], At[m][k], acc[ai][bj][m][n], 0, 0, 0); __builtin_amdgcn_s_setprio(0); } while (0)
; #define PG8_WAIT_V(n) asm volatile("s_waitcnt vmcnt(" #n ")" ::: "memory")
; #define PG8_WAIT_L(n) asm volatile("s_waitcnt lgkmcnt(" #n ")" ::: "memory")
; #define PG8_BAR __builtin_amdgcn_s_barrier()
; #define PG8_SCHED __builtin_amdgcn_sched_barrier(0)
; template <class Epi, class Sched, bool ALIGN_EPI = false, bool SP2 = false>
; __device__ __forceinline__ void gemm_phase(PG8_LAS unsigned char* lds, const Gemm g, const Sched S, const Epi E) {
;     ...
;             PG8_LDA(At, 1, 1); PG8_STAGE(PG8_SB(1, 0), b3, voffB); PG8_STAGE(PG8_SB(1, 1), b3 + hstep, voffB); PG8_STAGE(PG8_SA(1, 0), a3, voffA);
;             PG8_WAIT_V(8); PG8_WAIT_L(0); PG8_BAR; PG8_MMA(1, 0, At, B0); PG8_MMA(1, 1, At, B1); PG8_BAR; PG8_SCHED;
;     ...
;         }
;         if constexpr (ALIGN_EPI) { if (wr == 0) PG8_BAR; }
	s_add_i32 s18, s21, s61
	v_lshl_add_u64 v[140:141], v[140:141], 0, s[12:13]
	s_mov_b32 m0, s18
	ds_read_b128 v[202:205], v146 offset:49152
	ds_read_b128 v[206:209], v146 offset:50176
	ds_read_b128 v[210:213], v146 offset:51200
	ds_read_b128 v[214:217], v146 offset:52224
	ds_read_b128 v[218:221], v146 offset:53248
	ds_read_b128 v[222:225], v146 offset:54272
	ds_read_b128 v[226:229], v146 offset:55296
	ds_read_b128 v[230:233], v146 offset:56320
	global_load_lds_dwordx4 v[140:141], off
	v_lshl_add_u64 v[140:141], v[234:235], 0, s[12:13]
	s_add_i32 m0, s18, 0x2000
	s_add_i32 s18, s22, s61
	global_load_lds_dwordx4 v[140:141], off
	v_lshl_add_u64 v[140:141], v[236:237], 0, s[12:13]
	s_mov_b32 m0, s18
	s_nop 0
	global_load_lds_dwordx4 v[140:141], off
	v_lshl_add_u64 v[140:141], v[238:239], 0, s[12:13]
	s_add_i32 m0, s18, 0x2000
	s_nop 0
	global_load_lds_dwordx4 v[140:141], off
	v_lshl_add_u64 v[140:141], v[240:241], 0, s[12:13]
	s_mov_b32 m0, s73
	s_nop 0
	global_load_lds_dwordx4 v[140:141], off
	v_lshl_add_u64 v[140:141], v[242:243], 0, s[12:13]
	s_mov_b32 m0, s74
	s_nop 0
	global_load_lds_dwordx4 v[140:141], off
	s_waitcnt vmcnt(8)
	s_waitcnt lgkmcnt(0)
	s_barrier
	s_setprio 1
	v_mfma_f32_16x16x32_bf16 v[62:65], v[154:157], v[202:205], v[62:65]
	v_mfma_f32_16x16x32_bf16 v[54:57], v[162:165], v[202:205], v[54:57]
	v_mfma_f32_16x16x32_bf16 v[46:49], v[154:157], v[210:213], v[46:49]
	v_mfma_f32_16x16x32_bf16 v[38:41], v[162:165], v[210:213], v[38:41]
	v_mfma_f32_16x16x32_bf16 v[30:33], v[154:157], v[218:221], v[30:33]
	v_mfma_f32_16x16x32_bf16 v[22:25], v[162:165], v[218:221], v[22:25]
	v_mfma_f32_16x16x32_bf16 v[14:17], v[154:157], v[226:229], v[14:17]
	v_mfma_f32_16x16x32_bf16 v[6:9], v[162:165], v[226:229], v[6:9]
	v_mfma_f32_16x16x32_bf16 v[62:65], v[158:161], v[206:209], v[62:65]
	v_mfma_f32_16x16x32_bf16 v[54:57], v[166:169], v[206:209], v[54:57]
	v_mfma_f32_16x16x32_bf16 v[46:49], v[158:161], v[214:217], v[46:49]
	v_mfma_f32_16x16x32_bf16 v[38:41], v[166:169], v[214:217], v[38:41]
	v_mfma_f32_16x16x32_bf16 v[30:33], v[158:161], v[222:225], v[30:33]
	v_mfma_f32_16x16x32_bf16 v[22:25], v[166:169], v[222:225], v[22:25]
	v_mfma_f32_16x16x32_bf16 v[14:17], v[158:161], v[230:233], v[14:17]
	v_mfma_f32_16x16x32_bf16 v[6:9], v[166:169], v[230:233], v[6:9]
	s_setprio 0
	s_setprio 1
	v_mfma_f32_16x16x32_bf16 v[58:61], v[170:173], v[202:205], v[58:61]
	v_mfma_f32_16x16x32_bf16 v[50:53], v[182:185], v[202:205], v[50:53]
	v_mfma_f32_16x16x32_bf16 v[42:45], v[170:173], v[210:213], v[42:45]
	v_mfma_f32_16x16x32_bf16 v[34:37], v[182:185], v[210:213], v[34:37]
	v_mfma_f32_16x16x32_bf16 v[26:29], v[170:173], v[218:221], v[26:29]
	v_mfma_f32_16x16x32_bf16 v[18:21], v[182:185], v[218:221], v[18:21]
	v_mfma_f32_16x16x32_bf16 v[10:13], v[170:173], v[226:229], v[10:13]
	v_mfma_f32_16x16x32_bf16 v[2:5], v[182:185], v[226:229], v[2:5]
	v_mfma_f32_16x16x32_bf16 v[58:61], v[174:177], v[206:209], v[58:61]
	v_mfma_f32_16x16x32_bf16 v[50:53], v[198:201], v[206:209], v[50:53]
	v_mfma_f32_16x16x32_bf16 v[42:45], v[174:177], v[214:217], v[42:45]
	v_mfma_f32_16x16x32_bf16 v[34:37], v[198:201], v[214:217], v[34:37]
	v_mfma_f32_16x16x32_bf16 v[26:29], v[174:177], v[222:225], v[26:29]
	v_mfma_f32_16x16x32_bf16 v[18:21], v[198:201], v[222:225], v[18:21]
	v_mfma_f32_16x16x32_bf16 v[10:13], v[174:177], v[230:233], v[10:13]
	v_mfma_f32_16x16x32_bf16 v[2:5], v[198:201], v[230:233], v[2:5]
	s_setprio 0
	s_add_u32 s16, s16, 0x100
	s_addc_u32 s17, s17, 0
	s_add_u32 s14, s14, 0x100
	s_addc_u32 s15, s15, 0
	s_cmp_ge_u32 s20, s72
	s_mov_b32 s18, s20
	s_barrier
	s_cbranch_scc0 .LBB0_180
	s_and_b64 vcc, exec, s[56:57]
	s_cbranch_vccz .LBB0_183
	s_barrier

; #define PG8_STAGE(bufoff, gbase, voff) do { _Pragma("unroll") for (int _i = 0; _i < 2; ++_i) \
;         __builtin_amdgcn_global_load_lds((const unsigned*)((const char*)(gbase) + (voff)[_i]), (PG8_LAS unsigned*)(lds + (bufoff) + ldsw + _i * 8192), 16, 0, 0); } while (0)
; #define PG8_LDA(dst, b, h) do { _Pragma("unroll") for (int m = 0; m < 4; ++m) _Pragma("unroll") for (int k = 0; k < 2; ++k) dst[m][k] = *(const PG8_LAS bf16x8*)(lds + PG8_SA(b, h) + aoff + m * 2048 + k * 1024); } while (0)
; #define PG8_LDB(dst, b, h) do { _Pragma("unroll") for (int n = 0; n < 2; ++n) _Pragma("unroll") for (int k = 0; k < 2; ++k) dst[n][k] = *(const PG8_LAS bf16x8*)(lds + PG8_SB(b, h) + boff + n * 2048 + k * 1024); } while (0)
; #define PG8_MMA(ai, bj, At, Bt) do { __builtin_amdgcn_s_setprio(1); _Pragma("unroll") for (int m = 0; m < 4; ++m) _Pragma("unroll") for (int n = 0; n < 2; ++n) _Pragma("unroll") for (int k = 0; k < 2; ++k) \
;         acc[ai][bj][m][n] = __builtin_amdgcn_mfma_f32_16x16x32_bf16(Bt[n][k], At[m][k], acc[ai][bj][m][n], 0, 0, 0); __builtin_amdgcn_s_setprio(0); } while (0)
; #define PG8_WAIT_V(n) asm volatile("s_waitcnt vmcnt(" #n ")" ::: "memory")
; #define PG8_WAIT_L(n) asm volatile("s_waitcnt lgkmcnt(" #n ")" ::: "memory")
; #define PG8_BAR __builtin_amdgcn_s_barrier()
; #define PG8_SCHED __builtin_amdgcn_sched_barrier(0)
; template <class Epi, class Sched, bool ALIGN_EPI = false, bool SP2 = false>
; __device__ __forceinline__ void gemm_phase(PG8_LAS unsigned char* lds, const Gemm g, const Sched S, const Epi E) {
;     ...
;             const bool last = (t == nt - 2);
;             const char* a1 = cA + (size_t)(t + 1) * kstep;
;             const char* a2 = last ? nA : cA + (size_t)(t + 2) * kstep; const char* b2 = last ? nB : cB + (size_t)(t + 2) * kstep;
;             const char* a3 = a2 + kstep; const char* b3 = b2 + kstep;
;             if (last && has_next) S.a_ready(nxt);
;             if constexpr (SP2) {
;             PG8_LDB(B0, 0, 0); PG8_LDB(B1, 0, 1); PG8_SCHED; PG8_LDA(At, 0, 0); PG8_STAGE(PG8_SA(1, 1), a1 + hstep, voffA);
;             PG8_WAIT_V(8); PG8_WAIT_L(0); PG8_BAR; PG8_MMA(0, 0, At, B0); PG8_MMA(0, 1, At, B1); PG8_BAR; PG8_SCHED;
;             PG8_LDA(At, 0, 1); PG8_STAGE(PG8_SB(0, 0), b2, voffB); PG8_STAGE(PG8_SB(0, 1), b2 + hstep, voffB); PG8_STAGE(PG8_SA(0, 0), a2, voffA);
.LBB0_224:
	v_add_u32_e32 v141, 0x10000, v147
	ds_read_b128 v[154:157], v141
	ds_read_b128 v[158:161], v141 offset:1024
	ds_read_b128 v[162:165], v141 offset:2048
	ds_read_b128 v[166:169], v141 offset:3072
	v_add_u32_e32 v141, 0x14000, v147
	ds_read_b128 v[170:173], v141
	ds_read_b128 v[174:177], v141 offset:1024
	ds_read_b128 v[182:185], v141 offset:2048
	ds_read_b128 v[198:201], v141 offset:3072
	s_add_i32 s21, s20, 2
	s_add_u32 s22, s30, 0x80
	s_addc_u32 s23, s31, 0
	s_add_i32 s26, 0, 0x10000
	s_cmp_eq_u32 s81, s20
	s_cselect_b32 s75, s1, s23
	s_cselect_b32 s74, s0, s22
	s_cselect_b32 s23, s19, s15
	s_cselect_b32 s22, s18, s14
	s_add_i32 s20, 0, 0x14000
	v_lshl_add_u64 v[234:235], s[30:31], 0, v[136:137]
	s_add_i32 m0, s85, 0xc000
	ds_read_b128 v[202:205], v152
	ds_read_b128 v[206:209], v152 offset:1024
	ds_read_b128 v[210:213], v152 offset:2048
	ds_read_b128 v[214:217], v152 offset:3072
	ds_read_b128 v[218:221], v152 offset:4096
	ds_read_b128 v[222:225], v152 offset:5120
	ds_read_b128 v[226:229], v152 offset:6144
	ds_read_b128 v[230:233], v152 offset:7168
	global_load_lds_dwordx4 v[234:235], off
	v_lshl_add_u64 v[234:235], s[30:31], 0, v[138:139]
	s_add_i32 m0, s85, 0xe000
	s_nop 0
	global_load_lds_dwordx4 v[234:235], off
	s_waitcnt vmcnt(8)
	s_waitcnt lgkmcnt(0)
	s_barrier
	s_setprio 1
	v_mfma_f32_16x16x32_bf16 v[126:129], v[154:157], v[202:205], v[126:129]
	v_mfma_f32_16x16x32_bf16 v[122:125], v[162:165], v[202:205], v[122:125]
	v_mfma_f32_16x16x32_bf16 v[110:113], v[154:157], v[210:213], v[110:113]
	v_mfma_f32_16x16x32_bf16 v[106:109], v[162:165], v[210:213], v[106:109]
	v_mfma_f32_16x16x32_bf16 v[94:97], v[154:157], v[218:221], v[94:97]
	v_mfma_f32_16x16x32_bf16 v[90:93], v[162:165], v[218:221], v[90:93]
	v_mfma_f32_16x16x32_bf16 v[78:81], v[154:157], v[226:229], v[78:81]
	v_mfma_f32_16x16x32_bf16 v[74:77], v[162:165], v[226:229], v[74:77]
	v_mfma_f32_16x16x32_bf16 v[126:129], v[158:161], v[206:209], v[126:129]
	v_mfma_f32_16x16x32_bf16 v[122:125], v[166:169], v[206:209], v[122:125]
	v_mfma_f32_16x16x32_bf16 v[110:113], v[158:161], v[214:217], v[110:113]
	v_mfma_f32_16x16x32_bf16 v[106:109], v[166:169], v[214:217], v[106:109]
	v_mfma_f32_16x16x32_bf16 v[94:97], v[158:161], v[222:225], v[94:97]
	v_mfma_f32_16x16x32_bf16 v[90:93], v[166:169], v[222:225], v[90:93]
	v_mfma_f32_16x16x32_bf16 v[78:81], v[158:161], v[230:233], v[78:81]
	v_mfma_f32_16x16x32_bf16 v[74:77], v[166:169], v[230:233], v[74:77]
	s_setprio 0
	s_setprio 1
	v_mfma_f32_16x16x32_bf16 v[118:121], v[170:173], v[202:205], v[118:121]
	v_mfma_f32_16x16x32_bf16 v[114:117], v[182:185], v[202:205], v[114:117]
	v_mfma_f32_16x16x32_bf16 v[102:105], v[170:173], v[210:213], v[102:105]
	v_mfma_f32_16x16x32_bf16 v[98:101], v[182:185], v[210:213], v[98:101]
	v_mfma_f32_16x16x32_bf16 v[86:89], v[170:173], v[218:221], v[86:89]
	v_mfma_f32_16x16x32_bf16 v[82:85], v[182:185], v[218:221], v[82:85]
	v_mfma_f32_16x16x32_bf16 v[70:73], v[170:173], v[226:229], v[70:73]
	v_mfma_f32_16x16x32_bf16 v[66:69], v[182:185], v[226:229], v[66:69]
	v_mfma_f32_16x16x32_bf16 v[118:121], v[174:177], v[206:209], v[118:121]
	v_mfma_f32_16x16x32_bf16 v[114:117], v[198:201], v[206:209], v[114:117]
	v_mfma_f32_16x16x32_bf16 v[102:105], v[174:177], v[214:217], v[102:105]
	v_mfma_f32_16x16x32_bf16 v[98:101], v[198:201], v[214:217], v[98:101]
	v_mfma_f32_16x16x32_bf16 v[86:89], v[174:177], v[222:225], v[86:89]
	v_mfma_f32_16x16x32_bf16 v[82:85], v[198:201], v[222:225], v[82:85]
	v_mfma_f32_16x16x32_bf16 v[70:73], v[174:177], v[230:233], v[70:73]
	v_mfma_f32_16x16x32_bf16 v[66:69], v[198:201], v[230:233], v[66:69]
	s_setprio 0
	s_barrier
	s_add_i32 s26, s26, s84
	v_lshl_add_u64 v[234:235], s[22:23], 0, v[0:1]
	s_mov_b32 m0, s26
	ds_read_b128 v[202:205], v152 offset:16384
	ds_read_b128 v[206:209], v152 offset:17408
	ds_read_b128 v[210:213], v152 offset:18432
	ds_read_b128 v[214:217], v152 offset:19456
	ds_read_b128 v[218:221], v152 offset:20480
	ds_read_b128 v[222:225], v152 offset:21504
	ds_read_b128 v[226:229], v152 offset:22528
	ds_read_b128 v[230:233], v152 offset:23552
	global_load_lds_dwordx4 v[234:235], off
	s_add_i32 m0, s26, 0x2000
	v_lshl_add_u64 v[236:237], s[22:23], 0, v[134:135]
	s_add_u32 s22, s22, s52
	s_addc_u32 s23, s23, 0
	s_add_i32 s20, s20, s84
	global_load_lds_dwordx4 v[236:237], off
	v_lshl_add_u64 v[238:239], s[22:23], 0, v[0:1]
	s_mov_b32 m0, s20
	v_lshl_add_u64 v[240:241], s[22:23], 0, v[134:135]
	global_load_lds_dwordx4 v[238:239], off
	s_add_i32 m0, s20, 0x2000
	v_lshl_add_u64 v[242:243], s[74:75], 0, v[130:131]
	global_load_lds_dwordx4 v[240:241], off
	s_mov_b32 m0, s85
	v_lshl_add_u64 v[244:245], s[74:75], 0, v[132:133]
	global_load_lds_dwordx4 v[242:243], off
	s_mov_b32 m0, s86
	s_nop 0
	global_load_lds_dwordx4 v[244:245], off
	s_waitcnt vmcnt(8)
	s_waitcnt lgkmcnt(0)
	s_barrier
; #define PG8_STAGE(bufoff, gbase, voff) do { _Pragma("unroll") for (int _i = 0; _i < 2; ++_i) \
;         __builtin_amdgcn_global_load_lds((const unsigned*)((const char*)(gbase) + (voff)[_i]), (PG8_LAS unsigned*)(lds + (bufoff) + ldsw + _i * 8192), 16, 0, 0); } while (0)
; #define PG8_LDA(dst, b, h) do { _Pragma("unroll") for (int m = 0; m < 4; ++m) _Pragma("unroll") for (int k = 0; k < 2; ++k) dst[m][k] = *(const PG8_LAS bf16x8*)(lds + PG8_SA(b, h) + aoff + m * 2048 + k * 1024); } while (0)
; #define PG8_LDB(dst, b, h) do { _Pragma("unroll") for (int n = 0; n < 2; ++n) _Pragma("unroll") for (int k = 0; k < 2; ++k) dst[n][k] = *(const PG8_LAS bf16x8*)(lds + PG8_SB(b, h) + boff + n * 2048 + k * 1024); } while (0)
; #define PG8_MMA(ai, bj, At, Bt) do { __builtin_amdgcn_s_setprio(1); _Pragma("unroll") for (int m = 0; m < 4; ++m) _Pragma("unroll") for (int n = 0; n < 2; ++n) _Pragma("unroll") for (int k = 0; k < 2; ++k) \
;         acc[ai][bj][m][n] = __builtin_amdgcn_mfma_f32_16x16x32_bf16(Bt[n][k], At[m][k], acc[ai][bj][m][n], 0, 0, 0); __builtin_amdgcn_s_setprio(0); } while (0)
; #define PG8_WAIT_V(n) asm volatile("s_waitcnt vmcnt(" #n ")" ::: "memory")
; #define PG8_WAIT_L(n) asm volatile("s_waitcnt lgkmcnt(" #n ")" ::: "memory")
; #define PG8_BAR __builtin_amdgcn_s_barrier()
; #define PG8_SCHED __builtin_amdgcn_sched_barrier(0)
; template <class Epi, class Sched, bool ALIGN_EPI = false, bool SP2 = false>
; __device__ __forceinline__ void gemm_phase(PG8_LAS unsigned char* lds, const Gemm g, const Sched S, const Epi E) {
;     ...
;             PG8_WAIT_V(8); PG8_WAIT_L(0); PG8_BAR; PG8_MMA(1, 0, At, B0); PG8_MMA(1, 1, At, B1); PG8_BAR; PG8_SCHED;
;             PG8_LDB(B0, 1, 0); PG8_LDB(B1, 1, 1); PG8_SCHED; PG8_LDA(At, 1, 0); PG8_STAGE(PG8_SA(0, 1), a2 + hstep, voffA);
;             PG8_WAIT_V(8); PG8_WAIT_L(0); PG8_BAR; PG8_MMA(0, 0, At, B0); PG8_MMA(0, 1, At, B1); PG8_BAR; PG8_SCHED;
	s_setprio 1
	v_mfma_f32_16x16x32_bf16 v[62:65], v[154:157], v[202:205], v[62:65]
	v_mfma_f32_16x16x32_bf16 v[58:61], v[162:165], v[202:205], v[58:61]
	v_mfma_f32_16x16x32_bf16 v[46:49], v[154:157], v[210:213], v[46:49]
	v_mfma_f32_16x16x32_bf16 v[42:45], v[162:165], v[210:213], v[42:45]
	v_mfma_f32_16x16x32_bf16 v[30:33], v[154:157], v[218:221], v[30:33]
	v_mfma_f32_16x16x32_bf16 v[26:29], v[162:165], v[218:221], v[26:29]
	v_mfma_f32_16x16x32_bf16 v[14:17], v[154:157], v[226:229], v[14:17]
	v_mfma_f32_16x16x32_bf16 v[10:13], v[162:165], v[226:229], v[10:13]
	v_mfma_f32_16x16x32_bf16 v[62:65], v[158:161], v[206:209], v[62:65]
	v_mfma_f32_16x16x32_bf16 v[58:61], v[166:169], v[206:209], v[58:61]
	v_mfma_f32_16x16x32_bf16 v[46:49], v[158:161], v[214:217], v[46:49]
	v_mfma_f32_16x16x32_bf16 v[42:45], v[166:169], v[214:217], v[42:45]
	v_mfma_f32_16x16x32_bf16 v[30:33], v[158:161], v[222:225], v[30:33]
	v_mfma_f32_16x16x32_bf16 v[26:29], v[166:169], v[222:225], v[26:29]
	v_mfma_f32_16x16x32_bf16 v[14:17], v[158:161], v[230:233], v[14:17]
	v_mfma_f32_16x16x32_bf16 v[10:13], v[166:169], v[230:233], v[10:13]
	s_setprio 0
	s_setprio 1
	v_mfma_f32_16x16x32_bf16 v[54:57], v[170:173], v[202:205], v[54:57]
	v_mfma_f32_16x16x32_bf16 v[50:53], v[182:185], v[202:205], v[50:53]
	v_mfma_f32_16x16x32_bf16 v[38:41], v[170:173], v[210:213], v[38:41]
	v_mfma_f32_16x16x32_bf16 v[34:37], v[182:185], v[210:213], v[34:37]
	v_mfma_f32_16x16x32_bf16 v[22:25], v[170:173], v[218:221], v[22:25]
	v_mfma_f32_16x16x32_bf16 v[18:21], v[182:185], v[218:221], v[18:21]
	v_mfma_f32_16x16x32_bf16 v[6:9], v[170:173], v[226:229], v[6:9]
	v_mfma_f32_16x16x32_bf16 v[2:5], v[182:185], v[226:229], v[2:5]
	v_mfma_f32_16x16x32_bf16 v[54:57], v[174:177], v[206:209], v[54:57]
	v_mfma_f32_16x16x32_bf16 v[50:53], v[198:201], v[206:209], v[50:53]
	v_mfma_f32_16x16x32_bf16 v[38:41], v[174:177], v[214:217], v[38:41]
	v_mfma_f32_16x16x32_bf16 v[34:37], v[198:201], v[214:217], v[34:37]
	v_mfma_f32_16x16x32_bf16 v[22:25], v[174:177], v[222:225], v[22:25]
	v_mfma_f32_16x16x32_bf16 v[18:21], v[198:201], v[222:225], v[18:21]
	v_mfma_f32_16x16x32_bf16 v[6:9], v[174:177], v[230:233], v[6:9]
	v_mfma_f32_16x16x32_bf16 v[2:5], v[198:201], v[230:233], v[2:5]
	s_setprio 0
	s_barrier
	v_add_u32_e32 v141, 0x18000, v147
	ds_read_b128 v[154:157], v141
	ds_read_b128 v[158:161], v141 offset:1024
	ds_read_b128 v[162:165], v141 offset:2048
	ds_read_b128 v[166:169], v141 offset:3072
	v_add_u32_e32 v141, 0x1c000, v147
	ds_read_b128 v[170:173], v141
	ds_read_b128 v[174:177], v141 offset:1024
	ds_read_b128 v[182:185], v141 offset:2048
	ds_read_b128 v[198:201], v141 offset:3072
	s_add_i32 s20, 0, 0x18000
	s_add_i32 s26, 0, 0x1c000
	s_add_u32 s22, s74, s52
	s_addc_u32 s23, s75, 0
	s_mov_b32 m0, s87
	v_lshl_add_u64 v[246:247], s[22:23], 0, v[130:131]
	ds_read_b128 v[202:205], v152 offset:32768
	ds_read_b128 v[206:209], v152 offset:33792
	ds_read_b128 v[210:213], v152 offset:34816
	ds_read_b128 v[214:217], v152 offset:35840
	ds_read_b128 v[218:221], v152 offset:36864
	ds_read_b128 v[222:225], v152 offset:37888
	ds_read_b128 v[226:229], v152 offset:38912
	ds_read_b128 v[230:233], v152 offset:39936
	global_load_lds_dwordx4 v[246:247], off
	v_lshl_add_u64 v[246:247], s[22:23], 0, v[132:133]
	s_mov_b32 m0, s88
	s_nop 0
	global_load_lds_dwordx4 v[246:247], off
	s_waitcnt vmcnt(8)
	s_waitcnt lgkmcnt(0)
	s_barrier
	s_setprio 1
	v_mfma_f32_16x16x32_bf16 v[126:129], v[154:157], v[202:205], v[126:129]
	v_mfma_f32_16x16x32_bf16 v[122:125], v[162:165], v[202:205], v[122:125]
	v_mfma_f32_16x16x32_bf16 v[110:113], v[154:157], v[210:213], v[110:113]
	v_mfma_f32_16x16x32_bf16 v[106:109], v[162:165], v[210:213], v[106:109]
	v_mfma_f32_16x16x32_bf16 v[94:97], v[154:157], v[218:221], v[94:97]
	v_mfma_f32_16x16x32_bf16 v[90:93], v[162:165], v[218:221], v[90:93]
	v_mfma_f32_16x16x32_bf16 v[78:81], v[154:157], v[226:229], v[78:81]
	v_mfma_f32_16x16x32_bf16 v[74:77], v[162:165], v[226:229], v[74:77]
	v_mfma_f32_16x16x32_bf16 v[126:129], v[158:161], v[206:209], v[126:129]
	v_mfma_f32_16x16x32_bf16 v[122:125], v[166:169], v[206:209], v[122:125]
	v_mfma_f32_16x16x32_bf16 v[110:113], v[158:161], v[214:217], v[110:113]
	v_mfma_f32_16x16x32_bf16 v[106:109], v[166:169], v[214:217], v[106:109]
	v_mfma_f32_16x16x32_bf16 v[94:97], v[158:161], v[222:225], v[94:97]
	v_mfma_f32_16x16x32_bf16 v[90:93], v[166:169], v[222:225], v[90:93]
	v_mfma_f32_16x16x32_bf16 v[78:81], v[158:161], v[230:233], v[78:81]
	v_mfma_f32_16x16x32_bf16 v[74:77], v[166:169], v[230:233], v[74:77]
	s_setprio 0
	s_setprio 1
	v_mfma_f32_16x16x32_bf16 v[118:121], v[170:173], v[202:205], v[118:121]
	v_mfma_f32_16x16x32_bf16 v[114:117], v[182:185], v[202:205], v[114:117]
	v_mfma_f32_16x16x32_bf16 v[102:105], v[170:173], v[210:213], v[102:105]
	v_mfma_f32_16x16x32_bf16 v[98:101], v[182:185], v[210:213], v[98:101]
	v_mfma_f32_16x16x32_bf16 v[86:89], v[170:173], v[218:221], v[86:89]
	v_mfma_f32_16x16x32_bf16 v[82:85], v[182:185], v[218:221], v[82:85]
	v_mfma_f32_16x16x32_bf16 v[70:73], v[170:173], v[226:229], v[70:73]
	v_mfma_f32_16x16x32_bf16 v[66:69], v[182:185], v[226:229], v[66:69]
	v_mfma_f32_16x16x32_bf16 v[118:121], v[174:177], v[206:209], v[118:121]
	v_mfma_f32_16x16x32_bf16 v[114:117], v[198:201], v[206:209], v[114:117]
	v_mfma_f32_16x16x32_bf16 v[102:105], v[174:177], v[214:217], v[102:105]
	v_mfma_f32_16x16x32_bf16 v[98:101], v[198:201], v[214:217], v[98:101]
	v_mfma_f32_16x16x32_bf16 v[86:89], v[174:177], v[222:225], v[86:89]
	v_mfma_f32_16x16x32_bf16 v[82:85], v[198:201], v[222:225], v[82:85]
	v_mfma_f32_16x16x32_bf16 v[70:73], v[174:177], v[230:233], v[70:73]
	v_mfma_f32_16x16x32_bf16 v[66:69], v[198:201], v[230:233], v[66:69]
	s_setprio 0
	s_barrier
; #define PG8_STAGE(bufoff, gbase, voff) do { _Pragma("unroll") for (int _i = 0; _i < 2; ++_i) \
;         __builtin_amdgcn_global_load_lds((const unsigned*)((const char*)(gbase) + (voff)[_i]), (PG8_LAS unsigned*)(lds + (bufoff) + ldsw + _i * 8192), 16, 0, 0); } while (0)
; #define PG8_LDA(dst, b, h) do { _Pragma("unroll") for (int m = 0; m < 4; ++m) _Pragma("unroll") for (int k = 0; k < 2; ++k) dst[m][k] = *(const PG8_LAS bf16x8*)(lds + PG8_SA(b, h) + aoff + m * 2048 + k * 1024); } while (0)
; #define PG8_MMA(ai, bj, At, Bt) do { __builtin_amdgcn_s_setprio(1); _Pragma("unroll") for (int m = 0; m < 4; ++m) _Pragma("unroll") for (int n = 0; n < 2; ++n) _Pragma("unroll") for (int k = 0; k < 2; ++k) \
;         acc[ai][bj][m][n] = __builtin_amdgcn_mfma_f32_16x16x32_bf16(Bt[n][k], At[m][k], acc[ai][bj][m][n], 0, 0, 0); __builtin_amdgcn_s_setprio(0); } while (0)
; #define PG8_WAIT_V(n) asm volatile("s_waitcnt vmcnt(" #n ")" ::: "memory")
; #define PG8_WAIT_L(n) asm volatile("s_waitcnt lgkmcnt(" #n ")" ::: "memory")
; #define PG8_BAR __builtin_amdgcn_s_barrier()
; #define PG8_SCHED __builtin_amdgcn_sched_barrier(0)
; template <class Epi, class Sched, bool ALIGN_EPI = false, bool SP2 = false>
; __device__ __forceinline__ void gemm_phase(PG8_LAS unsigned char* lds, const Gemm g, const Sched S, const Epi E) {
;     ...
;             PG8_LDA(At, 1, 1); PG8_STAGE(PG8_SB(1, 0), b3, voffB); PG8_STAGE(PG8_SB(1, 1), b3 + hstep, voffB); PG8_STAGE(PG8_SA(1, 0), a3, voffA);
;             PG8_WAIT_V(8); PG8_WAIT_L(0); PG8_BAR; PG8_MMA(1, 0, At, B0); PG8_MMA(1, 1, At, B1); PG8_BAR; PG8_SCHED;
;     ...
;         }
;         if constexpr (ALIGN_EPI) { if (wr == 0) PG8_BAR; }
	s_add_i32 s20, s20, s84
	v_lshl_add_u64 v[234:235], v[234:235], 0, s[12:13]
	s_mov_b32 m0, s20
	ds_read_b128 v[202:205], v152 offset:49152
	ds_read_b128 v[206:209], v152 offset:50176
	ds_read_b128 v[210:213], v152 offset:51200
	ds_read_b128 v[214:217], v152 offset:52224
	ds_read_b128 v[218:221], v152 offset:53248
	ds_read_b128 v[222:225], v152 offset:54272
	ds_read_b128 v[226:229], v152 offset:55296
	ds_read_b128 v[230:233], v152 offset:56320
	global_load_lds_dwordx4 v[234:235], off
	v_lshl_add_u64 v[234:235], v[236:237], 0, s[12:13]
	s_add_i32 m0, s20, 0x2000
	s_add_i32 s20, s26, s84
	global_load_lds_dwordx4 v[234:235], off
	v_lshl_add_u64 v[234:235], v[238:239], 0, s[12:13]
	s_mov_b32 m0, s20
	s_nop 0
	global_load_lds_dwordx4 v[234:235], off
	v_lshl_add_u64 v[234:235], v[240:241], 0, s[12:13]
	s_add_i32 m0, s20, 0x2000
	s_nop 0
	global_load_lds_dwordx4 v[234:235], off
	v_lshl_add_u64 v[234:235], v[242:243], 0, s[12:13]
	s_mov_b32 m0, s3
	s_nop 0
	global_load_lds_dwordx4 v[234:235], off
	v_lshl_add_u64 v[234:235], v[244:245], 0, s[12:13]
	s_mov_b32 m0, s24
	s_nop 0
	global_load_lds_dwordx4 v[234:235], off
	s_waitcnt vmcnt(8)
	s_waitcnt lgkmcnt(0)
	s_barrier
	s_setprio 1
	v_mfma_f32_16x16x32_bf16 v[62:65], v[154:157], v[202:205], v[62:65]
	v_mfma_f32_16x16x32_bf16 v[58:61], v[162:165], v[202:205], v[58:61]
	v_mfma_f32_16x16x32_bf16 v[46:49], v[154:157], v[210:213], v[46:49]
	v_mfma_f32_16x16x32_bf16 v[42:45], v[162:165], v[210:213], v[42:45]
	v_mfma_f32_16x16x32_bf16 v[30:33], v[154:157], v[218:221], v[30:33]
	v_mfma_f32_16x16x32_bf16 v[26:29], v[162:165], v[218:221], v[26:29]
	v_mfma_f32_16x16x32_bf16 v[14:17], v[154:157], v[226:229], v[14:17]
	v_mfma_f32_16x16x32_bf16 v[10:13], v[162:165], v[226:229], v[10:13]
	v_mfma_f32_16x16x32_bf16 v[62:65], v[158:161], v[206:209], v[62:65]
	v_mfma_f32_16x16x32_bf16 v[58:61], v[166:169], v[206:209], v[58:61]
	v_mfma_f32_16x16x32_bf16 v[46:49], v[158:161], v[214:217], v[46:49]
	v_mfma_f32_16x16x32_bf16 v[42:45], v[166:169], v[214:217], v[42:45]
	v_mfma_f32_16x16x32_bf16 v[30:33], v[158:161], v[222:225], v[30:33]
	v_mfma_f32_16x16x32_bf16 v[26:29], v[166:169], v[222:225], v[26:29]
	v_mfma_f32_16x16x32_bf16 v[14:17], v[158:161], v[230:233], v[14:17]
	v_mfma_f32_16x16x32_bf16 v[10:13], v[166:169], v[230:233], v[10:13]
	s_setprio 0
	s_setprio 1
	v_mfma_f32_16x16x32_bf16 v[54:57], v[170:173], v[202:205], v[54:57]
	v_mfma_f32_16x16x32_bf16 v[50:53], v[182:185], v[202:205], v[50:53]
	v_mfma_f32_16x16x32_bf16 v[38:41], v[170:173], v[210:213], v[38:41]
	v_mfma_f32_16x16x32_bf16 v[34:37], v[182:185], v[210:213], v[34:37]
	v_mfma_f32_16x16x32_bf16 v[22:25], v[170:173], v[218:221], v[22:25]
	v_mfma_f32_16x16x32_bf16 v[18:21], v[182:185], v[218:221], v[18:21]
	v_mfma_f32_16x16x32_bf16 v[6:9], v[170:173], v[226:229], v[6:9]
	v_mfma_f32_16x16x32_bf16 v[2:5], v[182:185], v[226:229], v[2:5]
	v_mfma_f32_16x16x32_bf16 v[54:57], v[174:177], v[206:209], v[54:57]
	v_mfma_f32_16x16x32_bf16 v[50:53], v[198:201], v[206:209], v[50:53]
	v_mfma_f32_16x16x32_bf16 v[38:41], v[174:177], v[214:217], v[38:41]
	v_mfma_f32_16x16x32_bf16 v[34:37], v[198:201], v[214:217], v[34:37]
	v_mfma_f32_16x16x32_bf16 v[22:25], v[174:177], v[222:225], v[22:25]
	v_mfma_f32_16x16x32_bf16 v[18:21], v[198:201], v[222:225], v[18:21]
	v_mfma_f32_16x16x32_bf16 v[6:9], v[174:177], v[230:233], v[6:9]
	v_mfma_f32_16x16x32_bf16 v[2:5], v[198:201], v[230:233], v[2:5]
	s_setprio 0
	s_add_u32 s30, s30, 0x100
	s_addc_u32 s31, s31, 0
	s_add_u32 s14, s14, 0x100
	s_addc_u32 s15, s15, 0
	s_cmp_ge_u32 s21, s80
	s_mov_b32 s20, s21
	s_barrier
	s_cbranch_scc0 .LBB0_224
	s_and_b64 vcc, exec, s[16:17]
	s_cbranch_vccz .LBB0_227
	s_barrier

; #define PG8_STAGE(bufoff, gbase, voff) do { _Pragma("unroll") for (int _i = 0; _i < 2; ++_i) \
;         __builtin_amdgcn_global_load_lds((const unsigned*)((const char*)(gbase) + (voff)[_i]), (PG8_LAS unsigned*)(lds + (bufoff) + ldsw + _i * 8192), 16, 0, 0); } while (0)
; #define PG8_LDA(dst, b, h) do { _Pragma("unroll") for (int m = 0; m < 4; ++m) _Pragma("unroll") for (int k = 0; k < 2; ++k) dst[m][k] = *(const PG8_LAS bf16x8*)(lds + PG8_SA(b, h) + aoff + m * 2048 + k * 1024); } while (0)
; #define PG8_LDB(dst, b, h) do { _Pragma("unroll") for (int n = 0; n < 2; ++n) _Pragma("unroll") for (int k = 0; k < 2; ++k) dst[n][k] = *(const PG8_LAS bf16x8*)(lds + PG8_SB(b, h) + boff + n * 2048 + k * 1024); } while (0)
; #define PG8_MMA(ai, bj, At, Bt) do { __builtin_amdgcn_s_setprio(1); _Pragma("unroll") for (int m = 0; m < 4; ++m) _Pragma("unroll") for (int n = 0; n < 2; ++n) _Pragma("unroll") for (int k = 0; k < 2; ++k) \
;         acc[ai][bj][m][n] = __builtin_amdgcn_mfma_f32_16x16x32_bf16(Bt[n][k], At[m][k], acc[ai][bj][m][n], 0, 0, 0); __builtin_amdgcn_s_setprio(0); } while (0)
; #define PG8_WAIT_V(n) asm volatile("s_waitcnt vmcnt(" #n ")" ::: "memory")
; #define PG8_WAIT_L(n) asm volatile("s_waitcnt lgkmcnt(" #n ")" ::: "memory")
; #define PG8_BAR __builtin_amdgcn_s_barrier()
; #define PG8_SCHED __builtin_amdgcn_sched_barrier(0)
; template <class Epi, class Sched, bool ALIGN_EPI = false, bool SP2 = false>
; __device__ __forceinline__ void gemm_phase(PG8_LAS unsigned char* lds, const Gemm g, const Sched S, const Epi E) {
;     ...
;             const bool last = (t == nt - 2);
;             const char* a1 = cA + (size_t)(t + 1) * kstep;
;             const char* a2 = last ? nA : cA + (size_t)(t + 2) * kstep; const char* b2 = last ? nB : cB + (size_t)(t + 2) * kstep;
;             const char* a3 = a2 + kstep; const char* b3 = b2 + kstep;
;             if (last && has_next) S.a_ready(nxt);
;             if constexpr (SP2) {
;             PG8_LDB(B0, 0, 0); PG8_LDB(B1, 0, 1); PG8_SCHED; PG8_LDA(At, 0, 0); PG8_STAGE(PG8_SA(1, 1), a1 + hstep, voffA);
;             PG8_WAIT_V(8); PG8_WAIT_L(0); PG8_BAR; PG8_MMA(0, 0, At, B0); PG8_MMA(0, 1, At, B1); PG8_BAR; PG8_SCHED;
;             PG8_LDA(At, 0, 1); PG8_STAGE(PG8_SB(0, 0), b2, voffB); PG8_STAGE(PG8_SB(0, 1), b2 + hstep, voffB); PG8_STAGE(PG8_SA(0, 0), a2, voffA);
.LBB0_416:
	v_add_u32_e32 v158, 0x10000, v168
	v_add_u32_e32 v171, 0x14000, v168
	ds_read_b128 v[134:137], v158
	ds_read_b128 v[138:141], v158 offset:1024
	ds_read_b128 v[142:145], v158 offset:2048
	ds_read_b128 v[158:161], v158 offset:3072
	ds_read_b128 v[162:165], v171
	ds_read_b128 v[172:175], v171 offset:1024
	ds_read_b128 v[182:185], v171 offset:2048
	ds_read_b128 v[198:201], v171 offset:3072
	s_add_i32 s3, s14, 2
	s_add_u32 s15, s68, s16
	s_addc_u32 s18, s69, s17
	s_add_u32 s20, s66, s16
	s_addc_u32 s21, s67, s17
	s_add_i32 s22, 0, 0x10000
	s_cmp_eq_u32 s89, s14
	s_cselect_b32 s19, s1, s18
	s_cselect_b32 s18, s0, s15
	s_cselect_b32 s15, s71, s21
	s_cselect_b32 s14, s70, s20
	s_add_i32 s20, 0, 0x14000
	v_lshl_add_u64 v[176:177], s[68:69], 0, v[132:133]
	s_add_i32 m0, s80, 0xc000
	ds_read_b128 v[202:205], v170
	ds_read_b128 v[206:209], v170 offset:1024
	ds_read_b128 v[210:213], v170 offset:2048
	ds_read_b128 v[214:217], v170 offset:3072
	ds_read_b128 v[218:221], v170 offset:4096
	ds_read_b128 v[222:225], v170 offset:5120
	ds_read_b128 v[226:229], v170 offset:6144
	ds_read_b128 v[230:233], v170 offset:7168
	global_load_lds_dwordx4 v[176:177], off
	v_lshl_add_u64 v[176:177], s[68:69], 0, v[130:131]
	s_add_i32 m0, s80, 0xe000
	s_nop 0
	global_load_lds_dwordx4 v[176:177], off
	s_waitcnt vmcnt(8)
	s_waitcnt lgkmcnt(0)
	s_barrier
	s_setprio 1
	v_mfma_f32_16x16x32_bf16 v[58:61], v[134:137], v[202:205], v[58:61]
	v_mfma_f32_16x16x32_bf16 v[50:53], v[142:145], v[202:205], v[50:53]
	v_mfma_f32_16x16x32_bf16 v[14:17], v[134:137], v[210:213], v[14:17]
	v_mfma_f32_16x16x32_bf16 v[10:13], v[142:145], v[210:213], v[10:13]
	v_mfma_f32_16x16x32_bf16 v[30:33], v[134:137], v[218:221], v[30:33]
	v_mfma_f32_16x16x32_bf16 v[26:29], v[142:145], v[218:221], v[26:29]
	v_mfma_f32_16x16x32_bf16 v[46:49], v[134:137], v[226:229], v[46:49]
	v_mfma_f32_16x16x32_bf16 v[42:45], v[142:145], v[226:229], v[42:45]
	v_mfma_f32_16x16x32_bf16 v[58:61], v[138:141], v[206:209], v[58:61]
	v_mfma_f32_16x16x32_bf16 v[50:53], v[158:161], v[206:209], v[50:53]
	v_mfma_f32_16x16x32_bf16 v[14:17], v[138:141], v[214:217], v[14:17]
	v_mfma_f32_16x16x32_bf16 v[10:13], v[158:161], v[214:217], v[10:13]
	v_mfma_f32_16x16x32_bf16 v[30:33], v[138:141], v[222:225], v[30:33]
	v_mfma_f32_16x16x32_bf16 v[26:29], v[158:161], v[222:225], v[26:29]
	v_mfma_f32_16x16x32_bf16 v[46:49], v[138:141], v[230:233], v[46:49]
	v_mfma_f32_16x16x32_bf16 v[42:45], v[158:161], v[230:233], v[42:45]
	s_setprio 0
	s_setprio 1
	v_mfma_f32_16x16x32_bf16 v[6:9], v[162:165], v[202:205], v[6:9]
	v_mfma_f32_16x16x32_bf16 v[2:5], v[182:185], v[202:205], v[2:5]
	v_mfma_f32_16x16x32_bf16 v[22:25], v[162:165], v[210:213], v[22:25]
	v_mfma_f32_16x16x32_bf16 v[18:21], v[182:185], v[210:213], v[18:21]
	v_mfma_f32_16x16x32_bf16 v[38:41], v[162:165], v[218:221], v[38:41]
	v_mfma_f32_16x16x32_bf16 v[34:37], v[182:185], v[218:221], v[34:37]
	v_mfma_f32_16x16x32_bf16 v[62:65], v[162:165], v[226:229], v[62:65]
	v_mfma_f32_16x16x32_bf16 v[54:57], v[182:185], v[226:229], v[54:57]
	v_mfma_f32_16x16x32_bf16 v[6:9], v[172:175], v[206:209], v[6:9]
	v_mfma_f32_16x16x32_bf16 v[2:5], v[198:201], v[206:209], v[2:5]
	v_mfma_f32_16x16x32_bf16 v[22:25], v[172:175], v[214:217], v[22:25]
	v_mfma_f32_16x16x32_bf16 v[18:21], v[198:201], v[214:217], v[18:21]
	v_mfma_f32_16x16x32_bf16 v[38:41], v[172:175], v[222:225], v[38:41]
	v_mfma_f32_16x16x32_bf16 v[34:37], v[198:201], v[222:225], v[34:37]
	v_mfma_f32_16x16x32_bf16 v[62:65], v[172:175], v[230:233], v[62:65]
	v_mfma_f32_16x16x32_bf16 v[54:57], v[198:201], v[230:233], v[54:57]
	s_setprio 0
	s_barrier
	s_add_i32 s21, s22, s79
	v_lshl_add_u64 v[176:177], s[14:15], 0, v[148:149]
	s_mov_b32 m0, s21
	ds_read_b128 v[202:205], v170 offset:16384
	ds_read_b128 v[206:209], v170 offset:17408
	ds_read_b128 v[210:213], v170 offset:18432
	ds_read_b128 v[214:217], v170 offset:19456
	ds_read_b128 v[218:221], v170 offset:20480
	ds_read_b128 v[222:225], v170 offset:21504
	ds_read_b128 v[226:229], v170 offset:22528
	ds_read_b128 v[230:233], v170 offset:23552
	global_load_lds_dwordx4 v[176:177], off
	s_add_i32 m0, s21, 0x2000
	v_lshl_add_u64 v[234:235], s[14:15], 0, v[152:153]
	s_add_u32 s14, s14, s28
	s_addc_u32 s15, s15, 0
	s_add_i32 s20, s20, s79
	global_load_lds_dwordx4 v[234:235], off
	v_lshl_add_u64 v[236:237], s[14:15], 0, v[148:149]
	s_mov_b32 m0, s20
	v_lshl_add_u64 v[238:239], s[14:15], 0, v[152:153]
	global_load_lds_dwordx4 v[236:237], off
	s_add_i32 m0, s20, 0x2000
	v_lshl_add_u64 v[240:241], s[18:19], 0, v[146:147]
	global_load_lds_dwordx4 v[238:239], off
	s_mov_b32 m0, s80
	v_lshl_add_u64 v[242:243], s[18:19], 0, v[150:151]
	global_load_lds_dwordx4 v[240:241], off
	s_mov_b32 m0, s81
	s_nop 0
	global_load_lds_dwordx4 v[242:243], off
	s_waitcnt vmcnt(8)
	s_waitcnt lgkmcnt(0)
	s_barrier
; #define PG8_STAGE(bufoff, gbase, voff) do { _Pragma("unroll") for (int _i = 0; _i < 2; ++_i) \
;         __builtin_amdgcn_global_load_lds((const unsigned*)((const char*)(gbase) + (voff)[_i]), (PG8_LAS unsigned*)(lds + (bufoff) + ldsw + _i * 8192), 16, 0, 0); } while (0)
; #define PG8_LDA(dst, b, h) do { _Pragma("unroll") for (int m = 0; m < 4; ++m) _Pragma("unroll") for (int k = 0; k < 2; ++k) dst[m][k] = *(const PG8_LAS bf16x8*)(lds + PG8_SA(b, h) + aoff + m * 2048 + k * 1024); } while (0)
; #define PG8_LDB(dst, b, h) do { _Pragma("unroll") for (int n = 0; n < 2; ++n) _Pragma("unroll") for (int k = 0; k < 2; ++k) dst[n][k] = *(const PG8_LAS bf16x8*)(lds + PG8_SB(b, h) + boff + n * 2048 + k * 1024); } while (0)
; #define PG8_MMA(ai, bj, At, Bt) do { __builtin_amdgcn_s_setprio(1); _Pragma("unroll") for (int m = 0; m < 4; ++m) _Pragma("unroll") for (int n = 0; n < 2; ++n) _Pragma("unroll") for (int k = 0; k < 2; ++k) \
;         acc[ai][bj][m][n] = __builtin_amdgcn_mfma_f32_16x16x32_bf16(Bt[n][k], At[m][k], acc[ai][bj][m][n], 0, 0, 0); __builtin_amdgcn_s_setprio(0); } while (0)
; #define PG8_WAIT_V(n) asm volatile("s_waitcnt vmcnt(" #n ")" ::: "memory")
; #define PG8_WAIT_L(n) asm volatile("s_waitcnt lgkmcnt(" #n ")" ::: "memory")
; #define PG8_BAR __builtin_amdgcn_s_barrier()
; #define PG8_SCHED __builtin_amdgcn_sched_barrier(0)
; template <class Epi, class Sched, bool ALIGN_EPI = false, bool SP2 = false>
; __device__ __forceinline__ void gemm_phase(PG8_LAS unsigned char* lds, const Gemm g, const Sched S, const Epi E) {
;     ...
;             PG8_WAIT_V(8); PG8_WAIT_L(0); PG8_BAR; PG8_MMA(1, 0, At, B0); PG8_MMA(1, 1, At, B1); PG8_BAR; PG8_SCHED;
;             PG8_LDB(B0, 1, 0); PG8_LDB(B1, 1, 1); PG8_SCHED; PG8_LDA(At, 1, 0); PG8_STAGE(PG8_SA(0, 1), a2 + hstep, voffA);
;             PG8_WAIT_V(8); PG8_WAIT_L(0); PG8_BAR; PG8_MMA(0, 0, At, B0); PG8_MMA(0, 1, At, B1); PG8_BAR; PG8_SCHED;
	s_setprio 1
	v_mfma_f32_16x16x32_bf16 v[70:73], v[134:137], v[202:205], v[70:73]
	v_mfma_f32_16x16x32_bf16 v[66:69], v[142:145], v[202:205], v[66:69]
	v_mfma_f32_16x16x32_bf16 v[86:89], v[134:137], v[210:213], v[86:89]
	v_mfma_f32_16x16x32_bf16 v[82:85], v[142:145], v[210:213], v[82:85]
	v_mfma_f32_16x16x32_bf16 v[102:105], v[134:137], v[218:221], v[102:105]
	v_mfma_f32_16x16x32_bf16 v[98:101], v[142:145], v[218:221], v[98:101]
	v_mfma_f32_16x16x32_bf16 v[118:121], v[134:137], v[226:229], v[118:121]
	v_mfma_f32_16x16x32_bf16 v[114:117], v[142:145], v[226:229], v[114:117]
	v_mfma_f32_16x16x32_bf16 v[70:73], v[138:141], v[206:209], v[70:73]
	v_mfma_f32_16x16x32_bf16 v[66:69], v[158:161], v[206:209], v[66:69]
	v_mfma_f32_16x16x32_bf16 v[86:89], v[138:141], v[214:217], v[86:89]
	v_mfma_f32_16x16x32_bf16 v[82:85], v[158:161], v[214:217], v[82:85]
	v_mfma_f32_16x16x32_bf16 v[102:105], v[138:141], v[222:225], v[102:105]
	v_mfma_f32_16x16x32_bf16 v[98:101], v[158:161], v[222:225], v[98:101]
	v_mfma_f32_16x16x32_bf16 v[118:121], v[138:141], v[230:233], v[118:121]
	v_mfma_f32_16x16x32_bf16 v[114:117], v[158:161], v[230:233], v[114:117]
	s_setprio 0
	s_setprio 1
	v_mfma_f32_16x16x32_bf16 v[78:81], v[162:165], v[202:205], v[78:81]
	v_mfma_f32_16x16x32_bf16 v[74:77], v[182:185], v[202:205], v[74:77]
	v_mfma_f32_16x16x32_bf16 v[94:97], v[162:165], v[210:213], v[94:97]
	v_mfma_f32_16x16x32_bf16 v[90:93], v[182:185], v[210:213], v[90:93]
	v_mfma_f32_16x16x32_bf16 v[110:113], v[162:165], v[218:221], v[110:113]
	v_mfma_f32_16x16x32_bf16 v[106:109], v[182:185], v[218:221], v[106:109]
	v_mfma_f32_16x16x32_bf16 v[126:129], v[162:165], v[226:229], v[126:129]
	v_mfma_f32_16x16x32_bf16 v[122:125], v[182:185], v[226:229], v[122:125]
	v_mfma_f32_16x16x32_bf16 v[78:81], v[172:175], v[206:209], v[78:81]
	v_mfma_f32_16x16x32_bf16 v[74:77], v[198:201], v[206:209], v[74:77]
	v_mfma_f32_16x16x32_bf16 v[94:97], v[172:175], v[214:217], v[94:97]
	v_mfma_f32_16x16x32_bf16 v[90:93], v[198:201], v[214:217], v[90:93]
	v_mfma_f32_16x16x32_bf16 v[110:113], v[172:175], v[222:225], v[110:113]
	v_mfma_f32_16x16x32_bf16 v[106:109], v[198:201], v[222:225], v[106:109]
	v_mfma_f32_16x16x32_bf16 v[126:129], v[172:175], v[230:233], v[126:129]
	v_mfma_f32_16x16x32_bf16 v[122:125], v[198:201], v[230:233], v[122:125]
	s_setprio 0
	s_barrier
	v_add_u32_e32 v158, 0x18000, v168
	v_add_u32_e32 v171, 0x1c000, v168
	ds_read_b128 v[134:137], v158
	ds_read_b128 v[138:141], v158 offset:1024
	ds_read_b128 v[142:145], v158 offset:2048
	ds_read_b128 v[158:161], v158 offset:3072
	ds_read_b128 v[162:165], v171
	ds_read_b128 v[172:175], v171 offset:1024
	ds_read_b128 v[182:185], v171 offset:2048
	ds_read_b128 v[198:201], v171 offset:3072
	s_add_i32 s20, 0, 0x18000
	s_add_i32 s21, 0, 0x1c000
	s_add_u32 s14, s18, s28
	s_addc_u32 s15, s19, 0
	s_mov_b32 m0, s82
	v_lshl_add_u64 v[244:245], s[14:15], 0, v[146:147]
	ds_read_b128 v[202:205], v170 offset:32768
	ds_read_b128 v[206:209], v170 offset:33792
	ds_read_b128 v[210:213], v170 offset:34816
	ds_read_b128 v[214:217], v170 offset:35840
	ds_read_b128 v[218:221], v170 offset:36864
	ds_read_b128 v[222:225], v170 offset:37888
	ds_read_b128 v[226:229], v170 offset:38912
	ds_read_b128 v[230:233], v170 offset:39936
	global_load_lds_dwordx4 v[244:245], off
	v_lshl_add_u64 v[244:245], s[14:15], 0, v[150:151]
	s_mov_b32 m0, s83
	s_nop 0
	global_load_lds_dwordx4 v[244:245], off
	s_waitcnt vmcnt(8)
	s_waitcnt lgkmcnt(0)
	s_barrier
	s_setprio 1
	v_mfma_f32_16x16x32_bf16 v[58:61], v[134:137], v[202:205], v[58:61]
	v_mfma_f32_16x16x32_bf16 v[50:53], v[142:145], v[202:205], v[50:53]
	v_mfma_f32_16x16x32_bf16 v[14:17], v[134:137], v[210:213], v[14:17]
	v_mfma_f32_16x16x32_bf16 v[10:13], v[142:145], v[210:213], v[10:13]
	v_mfma_f32_16x16x32_bf16 v[30:33], v[134:137], v[218:221], v[30:33]
	v_mfma_f32_16x16x32_bf16 v[26:29], v[142:145], v[218:221], v[26:29]
	v_mfma_f32_16x16x32_bf16 v[46:49], v[134:137], v[226:229], v[46:49]
	v_mfma_f32_16x16x32_bf16 v[42:45], v[142:145], v[226:229], v[42:45]
	v_mfma_f32_16x16x32_bf16 v[58:61], v[138:141], v[206:209], v[58:61]
	v_mfma_f32_16x16x32_bf16 v[50:53], v[158:161], v[206:209], v[50:53]
	v_mfma_f32_16x16x32_bf16 v[14:17], v[138:141], v[214:217], v[14:17]
	v_mfma_f32_16x16x32_bf16 v[10:13], v[158:161], v[214:217], v[10:13]
	v_mfma_f32_16x16x32_bf16 v[30:33], v[138:141], v[222:225], v[30:33]
	v_mfma_f32_16x16x32_bf16 v[26:29], v[158:161], v[222:225], v[26:29]
	v_mfma_f32_16x16x32_bf16 v[46:49], v[138:141], v[230:233], v[46:49]
	v_mfma_f32_16x16x32_bf16 v[42:45], v[158:161], v[230:233], v[42:45]
	s_setprio 0
	s_setprio 1
	v_mfma_f32_16x16x32_bf16 v[6:9], v[162:165], v[202:205], v[6:9]
	v_mfma_f32_16x16x32_bf16 v[2:5], v[182:185], v[202:205], v[2:5]
	v_mfma_f32_16x16x32_bf16 v[22:25], v[162:165], v[210:213], v[22:25]
	v_mfma_f32_16x16x32_bf16 v[18:21], v[182:185], v[210:213], v[18:21]
	v_mfma_f32_16x16x32_bf16 v[38:41], v[162:165], v[218:221], v[38:41]
	v_mfma_f32_16x16x32_bf16 v[34:37], v[182:185], v[218:221], v[34:37]
	v_mfma_f32_16x16x32_bf16 v[62:65], v[162:165], v[226:229], v[62:65]
	v_mfma_f32_16x16x32_bf16 v[54:57], v[182:185], v[226:229], v[54:57]
	v_mfma_f32_16x16x32_bf16 v[6:9], v[172:175], v[206:209], v[6:9]
	v_mfma_f32_16x16x32_bf16 v[2:5], v[198:201], v[206:209], v[2:5]
	v_mfma_f32_16x16x32_bf16 v[22:25], v[172:175], v[214:217], v[22:25]
	v_mfma_f32_16x16x32_bf16 v[18:21], v[198:201], v[214:217], v[18:21]
	v_mfma_f32_16x16x32_bf16 v[38:41], v[172:175], v[222:225], v[38:41]
	v_mfma_f32_16x16x32_bf16 v[34:37], v[198:201], v[222:225], v[34:37]
	v_mfma_f32_16x16x32_bf16 v[62:65], v[172:175], v[230:233], v[62:65]
	v_mfma_f32_16x16x32_bf16 v[54:57], v[198:201], v[230:233], v[54:57]
	s_setprio 0
	s_barrier
; #define PG8_STAGE(bufoff, gbase, voff) do { _Pragma("unroll") for (int _i = 0; _i < 2; ++_i) \
;         __builtin_amdgcn_global_load_lds((const unsigned*)((const char*)(gbase) + (voff)[_i]), (PG8_LAS unsigned*)(lds + (bufoff) + ldsw + _i * 8192), 16, 0, 0); } while (0)
; #define PG8_LDA(dst, b, h) do { _Pragma("unroll") for (int m = 0; m < 4; ++m) _Pragma("unroll") for (int k = 0; k < 2; ++k) dst[m][k] = *(const PG8_LAS bf16x8*)(lds + PG8_SA(b, h) + aoff + m * 2048 + k * 1024); } while (0)
; #define PG8_MMA(ai, bj, At, Bt) do { __builtin_amdgcn_s_setprio(1); _Pragma("unroll") for (int m = 0; m < 4; ++m) _Pragma("unroll") for (int n = 0; n < 2; ++n) _Pragma("unroll") for (int k = 0; k < 2; ++k) \
;         acc[ai][bj][m][n] = __builtin_amdgcn_mfma_f32_16x16x32_bf16(Bt[n][k], At[m][k], acc[ai][bj][m][n], 0, 0, 0); __builtin_amdgcn_s_setprio(0); } while (0)
; #define PG8_WAIT_V(n) asm volatile("s_waitcnt vmcnt(" #n ")" ::: "memory")
; #define PG8_WAIT_L(n) asm volatile("s_waitcnt lgkmcnt(" #n ")" ::: "memory")
; #define PG8_BAR __builtin_amdgcn_s_barrier()
; #define PG8_SCHED __builtin_amdgcn_sched_barrier(0)
; template <class Epi, class Sched, bool ALIGN_EPI = false, bool SP2 = false>
; __device__ __forceinline__ void gemm_phase(PG8_LAS unsigned char* lds, const Gemm g, const Sched S, const Epi E) {
;     ...
;             PG8_LDA(At, 1, 1); PG8_STAGE(PG8_SB(1, 0), b3, voffB); PG8_STAGE(PG8_SB(1, 1), b3 + hstep, voffB); PG8_STAGE(PG8_SA(1, 0), a3, voffA);
;             PG8_WAIT_V(8); PG8_WAIT_L(0); PG8_BAR; PG8_MMA(1, 0, At, B0); PG8_MMA(1, 1, At, B1); PG8_BAR; PG8_SCHED;
;     ...
;         }
;         if constexpr (ALIGN_EPI) { if (wr == 0) PG8_BAR; }
	s_add_i32 s14, s20, s79
	v_lshl_add_u64 v[176:177], v[176:177], 0, s[12:13]
	s_mov_b32 m0, s14
	ds_read_b128 v[202:205], v170 offset:49152
	ds_read_b128 v[206:209], v170 offset:50176
	ds_read_b128 v[210:213], v170 offset:51200
	ds_read_b128 v[214:217], v170 offset:52224
	ds_read_b128 v[218:221], v170 offset:53248
	ds_read_b128 v[222:225], v170 offset:54272
	ds_read_b128 v[226:229], v170 offset:55296
	ds_read_b128 v[230:233], v170 offset:56320
	global_load_lds_dwordx4 v[176:177], off
	v_lshl_add_u64 v[176:177], v[234:235], 0, s[12:13]
	s_add_i32 m0, s14, 0x2000
	s_add_i32 s14, s21, s79
	global_load_lds_dwordx4 v[176:177], off
	v_lshl_add_u64 v[176:177], v[236:237], 0, s[12:13]
	s_mov_b32 m0, s14
	s_nop 0
	global_load_lds_dwordx4 v[176:177], off
	v_lshl_add_u64 v[176:177], v[238:239], 0, s[12:13]
	s_add_i32 m0, s14, 0x2000
	s_nop 0
	global_load_lds_dwordx4 v[176:177], off
	v_lshl_add_u64 v[176:177], v[240:241], 0, s[12:13]
	s_mov_b32 m0, s84
	s_nop 0
	global_load_lds_dwordx4 v[176:177], off
	v_lshl_add_u64 v[176:177], v[242:243], 0, s[12:13]
	s_mov_b32 m0, s85
	s_nop 0
	global_load_lds_dwordx4 v[176:177], off
	s_waitcnt vmcnt(8)
	s_waitcnt lgkmcnt(0)
	s_barrier
	s_setprio 1
	v_mfma_f32_16x16x32_bf16 v[70:73], v[134:137], v[202:205], v[70:73]
	v_mfma_f32_16x16x32_bf16 v[66:69], v[142:145], v[202:205], v[66:69]
	v_mfma_f32_16x16x32_bf16 v[86:89], v[134:137], v[210:213], v[86:89]
	v_mfma_f32_16x16x32_bf16 v[82:85], v[142:145], v[210:213], v[82:85]
	v_mfma_f32_16x16x32_bf16 v[102:105], v[134:137], v[218:221], v[102:105]
	v_mfma_f32_16x16x32_bf16 v[98:101], v[142:145], v[218:221], v[98:101]
	v_mfma_f32_16x16x32_bf16 v[118:121], v[134:137], v[226:229], v[118:121]
	v_mfma_f32_16x16x32_bf16 v[114:117], v[142:145], v[226:229], v[114:117]
	v_mfma_f32_16x16x32_bf16 v[70:73], v[138:141], v[206:209], v[70:73]
	v_mfma_f32_16x16x32_bf16 v[66:69], v[158:161], v[206:209], v[66:69]
	v_mfma_f32_16x16x32_bf16 v[86:89], v[138:141], v[214:217], v[86:89]
	v_mfma_f32_16x16x32_bf16 v[82:85], v[158:161], v[214:217], v[82:85]
	v_mfma_f32_16x16x32_bf16 v[102:105], v[138:141], v[222:225], v[102:105]
	v_mfma_f32_16x16x32_bf16 v[98:101], v[158:161], v[222:225], v[98:101]
	v_mfma_f32_16x16x32_bf16 v[118:121], v[138:141], v[230:233], v[118:121]
	v_mfma_f32_16x16x32_bf16 v[114:117], v[158:161], v[230:233], v[114:117]
	s_setprio 0
	s_setprio 1
	v_mfma_f32_16x16x32_bf16 v[78:81], v[162:165], v[202:205], v[78:81]
	v_mfma_f32_16x16x32_bf16 v[74:77], v[182:185], v[202:205], v[74:77]
	v_mfma_f32_16x16x32_bf16 v[94:97], v[162:165], v[210:213], v[94:97]
	v_mfma_f32_16x16x32_bf16 v[90:93], v[182:185], v[210:213], v[90:93]
	v_mfma_f32_16x16x32_bf16 v[110:113], v[162:165], v[218:221], v[110:113]
	v_mfma_f32_16x16x32_bf16 v[106:109], v[182:185], v[218:221], v[106:109]
	v_mfma_f32_16x16x32_bf16 v[126:129], v[162:165], v[226:229], v[126:129]
	v_mfma_f32_16x16x32_bf16 v[122:125], v[182:185], v[226:229], v[122:125]
	v_mfma_f32_16x16x32_bf16 v[78:81], v[172:175], v[206:209], v[78:81]
	v_mfma_f32_16x16x32_bf16 v[74:77], v[198:201], v[206:209], v[74:77]
	v_mfma_f32_16x16x32_bf16 v[94:97], v[172:175], v[214:217], v[94:97]
	v_mfma_f32_16x16x32_bf16 v[90:93], v[198:201], v[214:217], v[90:93]
	v_mfma_f32_16x16x32_bf16 v[110:113], v[172:175], v[222:225], v[110:113]
	v_mfma_f32_16x16x32_bf16 v[106:109], v[198:201], v[222:225], v[106:109]
	v_mfma_f32_16x16x32_bf16 v[126:129], v[172:175], v[230:233], v[126:129]
	v_mfma_f32_16x16x32_bf16 v[122:125], v[198:201], v[230:233], v[122:125]
	s_setprio 0
	s_add_u32 s16, s16, 0x100
	s_addc_u32 s17, s17, 0
	v_lshl_add_u64 v[132:133], v[132:133], 0, s[30:31]
	v_lshl_add_u64 v[130:131], v[130:131], 0, s[30:31]
	s_cmp_ge_u32 s3, s88
	s_mov_b32 s14, s3
	s_barrier
	s_cbranch_scc0 .LBB0_416
	s_and_b64 vcc, exec, s[62:63]
	s_cbranch_vccz .LBB0_419
	s_barrier

; #define PG8_STAGE(bufoff, gbase, voff) do { _Pragma("unroll") for (int _i = 0; _i < 2; ++_i) \
;         __builtin_amdgcn_global_load_lds((const unsigned*)((const char*)(gbase) + (voff)[_i]), (PG8_LAS unsigned*)(lds + (bufoff) + ldsw + _i * 8192), 16, 0, 0); } while (0)
; #define PG8_LDA(dst, b, h) do { _Pragma("unroll") for (int m = 0; m < 4; ++m) _Pragma("unroll") for (int k = 0; k < 2; ++k) dst[m][k] = *(const PG8_LAS bf16x8*)(lds + PG8_SA(b, h) + aoff + m * 2048 + k * 1024); } while (0)
; #define PG8_LDB(dst, b, h) do { _Pragma("unroll") for (int n = 0; n < 2; ++n) _Pragma("unroll") for (int k = 0; k < 2; ++k) dst[n][k] = *(const PG8_LAS bf16x8*)(lds + PG8_SB(b, h) + boff + n * 2048 + k * 1024); } while (0)
; #define PG8_MMA(ai, bj, At, Bt) do { __builtin_amdgcn_s_setprio(1); _Pragma("unroll") for (int m = 0; m < 4; ++m) _Pragma("unroll") for (int n = 0; n < 2; ++n) _Pragma("unroll") for (int k = 0; k < 2; ++k) \
;         acc[ai][bj][m][n] = __builtin_amdgcn_mfma_f32_16x16x32_bf16(Bt[n][k], At[m][k], acc[ai][bj][m][n], 0, 0, 0); __builtin_amdgcn_s_setprio(0); } while (0)
; #define PG8_WAIT_V(n) asm volatile("s_waitcnt vmcnt(" #n ")" ::: "memory")
; #define PG8_WAIT_L(n) asm volatile("s_waitcnt lgkmcnt(" #n ")" ::: "memory")
; #define PG8_BAR __builtin_amdgcn_s_barrier()
; #define PG8_SCHED __builtin_amdgcn_sched_barrier(0)
; template <class Epi, class Sched, bool ALIGN_EPI = false, bool SP2 = false>
; __device__ __forceinline__ void gemm_phase(PG8_LAS unsigned char* lds, const Gemm g, const Sched S, const Epi E) {
;     ...
;             const bool last = (t == nt - 2);
;             const char* a1 = cA + (size_t)(t + 1) * kstep;
;             const char* a2 = last ? nA : cA + (size_t)(t + 2) * kstep; const char* b2 = last ? nB : cB + (size_t)(t + 2) * kstep;
;             const char* a3 = a2 + kstep; const char* b3 = b2 + kstep;
;             if (last && has_next) S.a_ready(nxt);
;             if constexpr (SP2) {
;             PG8_LDB(B0, 0, 0); PG8_LDB(B1, 0, 1); PG8_SCHED; PG8_LDA(At, 0, 0); PG8_STAGE(PG8_SA(1, 1), a1 + hstep, voffA);
;             PG8_WAIT_V(8); PG8_WAIT_L(0); PG8_BAR; PG8_MMA(0, 0, At, B0); PG8_MMA(0, 1, At, B1); PG8_BAR; PG8_SCHED;
;             PG8_LDA(At, 0, 1); PG8_STAGE(PG8_SB(0, 0), b2, voffB); PG8_STAGE(PG8_SB(0, 1), b2 + hstep, voffB); PG8_STAGE(PG8_SA(0, 0), a2, voffA);
.LBB0_538:
	v_add_u32_e32 v155, 0x10000, v152
	ds_read_b128 v[146:149], v155
	ds_read_b128 v[156:159], v155 offset:1024
	ds_read_b128 v[160:163], v155 offset:2048
	ds_read_b128 v[164:167], v155 offset:3072
	v_add_u32_e32 v155, 0x14000, v152
	ds_read_b128 v[168:171], v155
	ds_read_b128 v[172:175], v155 offset:1024
	ds_read_b128 v[182:185], v155 offset:2048
	ds_read_b128 v[198:201], v155 offset:3072
	s_add_i32 s3, s14, 2
	s_add_u32 s15, s68, s16
	s_addc_u32 s18, s69, s17
	s_add_u32 s20, s66, s16
	s_addc_u32 s21, s67, s17
	s_add_i32 s22, 0, 0x10000
	s_cmp_eq_u32 s81, s14
	s_cselect_b32 s19, s1, s18
	s_cselect_b32 s18, s0, s15
	s_cselect_b32 s15, s55, s21
	s_cselect_b32 s14, s54, s20
	s_add_i32 s20, 0, 0x14000
	v_lshl_add_u64 v[176:177], s[68:69], 0, v[144:145]
	s_add_i32 m0, s72, 0xc000
	ds_read_b128 v[202:205], v154
	ds_read_b128 v[206:209], v154 offset:1024
	ds_read_b128 v[210:213], v154 offset:2048
	ds_read_b128 v[214:217], v154 offset:3072
	ds_read_b128 v[218:221], v154 offset:4096
	ds_read_b128 v[222:225], v154 offset:5120
	ds_read_b128 v[226:229], v154 offset:6144
	ds_read_b128 v[230:233], v154 offset:7168
	global_load_lds_dwordx4 v[176:177], off
	v_lshl_add_u64 v[176:177], s[68:69], 0, v[142:143]
	s_add_i32 m0, s72, 0xe000
	s_nop 0
	global_load_lds_dwordx4 v[176:177], off
	s_waitcnt vmcnt(8)
	s_waitcnt lgkmcnt(0)
	s_barrier
	s_setprio 1
	v_mfma_f32_16x16x32_bf16 v[62:65], v[146:149], v[202:205], v[62:65]
	v_mfma_f32_16x16x32_bf16 v[54:57], v[160:163], v[202:205], v[54:57]
	v_mfma_f32_16x16x32_bf16 v[14:17], v[146:149], v[210:213], v[14:17]
	v_mfma_f32_16x16x32_bf16 v[10:13], v[160:163], v[210:213], v[10:13]
	v_mfma_f32_16x16x32_bf16 v[30:33], v[146:149], v[218:221], v[30:33]
	v_mfma_f32_16x16x32_bf16 v[26:29], v[160:163], v[218:221], v[26:29]
	v_mfma_f32_16x16x32_bf16 v[46:49], v[146:149], v[226:229], v[46:49]
	v_mfma_f32_16x16x32_bf16 v[42:45], v[160:163], v[226:229], v[42:45]
	v_mfma_f32_16x16x32_bf16 v[62:65], v[156:159], v[206:209], v[62:65]
	v_mfma_f32_16x16x32_bf16 v[54:57], v[164:167], v[206:209], v[54:57]
	v_mfma_f32_16x16x32_bf16 v[14:17], v[156:159], v[214:217], v[14:17]
	v_mfma_f32_16x16x32_bf16 v[10:13], v[164:167], v[214:217], v[10:13]
	v_mfma_f32_16x16x32_bf16 v[30:33], v[156:159], v[222:225], v[30:33]
	v_mfma_f32_16x16x32_bf16 v[26:29], v[164:167], v[222:225], v[26:29]
	v_mfma_f32_16x16x32_bf16 v[46:49], v[156:159], v[230:233], v[46:49]
	v_mfma_f32_16x16x32_bf16 v[42:45], v[164:167], v[230:233], v[42:45]
	s_setprio 0
	s_setprio 1
	v_mfma_f32_16x16x32_bf16 v[6:9], v[168:171], v[202:205], v[6:9]
	v_mfma_f32_16x16x32_bf16 v[2:5], v[182:185], v[202:205], v[2:5]
	v_mfma_f32_16x16x32_bf16 v[22:25], v[168:171], v[210:213], v[22:25]
	v_mfma_f32_16x16x32_bf16 v[18:21], v[182:185], v[210:213], v[18:21]
	v_mfma_f32_16x16x32_bf16 v[38:41], v[168:171], v[218:221], v[38:41]
	v_mfma_f32_16x16x32_bf16 v[34:37], v[182:185], v[218:221], v[34:37]
	v_mfma_f32_16x16x32_bf16 v[58:61], v[168:171], v[226:229], v[58:61]
	v_mfma_f32_16x16x32_bf16 v[50:53], v[182:185], v[226:229], v[50:53]
	v_mfma_f32_16x16x32_bf16 v[6:9], v[172:175], v[206:209], v[6:9]
	v_mfma_f32_16x16x32_bf16 v[2:5], v[198:201], v[206:209], v[2:5]
	v_mfma_f32_16x16x32_bf16 v[22:25], v[172:175], v[214:217], v[22:25]
	v_mfma_f32_16x16x32_bf16 v[18:21], v[198:201], v[214:217], v[18:21]
	v_mfma_f32_16x16x32_bf16 v[38:41], v[172:175], v[222:225], v[38:41]
	v_mfma_f32_16x16x32_bf16 v[34:37], v[198:201], v[222:225], v[34:37]
	v_mfma_f32_16x16x32_bf16 v[58:61], v[172:175], v[230:233], v[58:61]
	v_mfma_f32_16x16x32_bf16 v[50:53], v[198:201], v[230:233], v[50:53]
	s_setprio 0
	s_barrier
	s_add_i32 s21, s22, s71
	v_lshl_add_u64 v[176:177], s[14:15], 0, v[0:1]
	s_mov_b32 m0, s21
	ds_read_b128 v[202:205], v154 offset:16384
	ds_read_b128 v[206:209], v154 offset:17408
	ds_read_b128 v[210:213], v154 offset:18432
	ds_read_b128 v[214:217], v154 offset:19456
	ds_read_b128 v[218:221], v154 offset:20480
	ds_read_b128 v[222:225], v154 offset:21504
	ds_read_b128 v[226:229], v154 offset:22528
	ds_read_b128 v[230:233], v154 offset:23552
	global_load_lds_dwordx4 v[176:177], off
	s_add_i32 m0, s21, 0x2000
	v_lshl_add_u64 v[234:235], s[14:15], 0, v[134:135]
	s_add_u32 s14, s14, s28
	s_addc_u32 s15, s15, 0
	s_add_i32 s20, s20, s71
	global_load_lds_dwordx4 v[234:235], off
	v_lshl_add_u64 v[236:237], s[14:15], 0, v[0:1]
	s_mov_b32 m0, s20
	v_lshl_add_u64 v[238:239], s[14:15], 0, v[134:135]
	global_load_lds_dwordx4 v[236:237], off
	s_add_i32 m0, s20, 0x2000
	v_lshl_add_u64 v[240:241], s[18:19], 0, v[130:131]
	global_load_lds_dwordx4 v[238:239], off
	s_mov_b32 m0, s72
	v_lshl_add_u64 v[242:243], s[18:19], 0, v[132:133]
	global_load_lds_dwordx4 v[240:241], off
	s_mov_b32 m0, s73
	s_nop 0
	global_load_lds_dwordx4 v[242:243], off
	s_waitcnt vmcnt(8)
	s_waitcnt lgkmcnt(0)
	s_barrier
; #define PG8_STAGE(bufoff, gbase, voff) do { _Pragma("unroll") for (int _i = 0; _i < 2; ++_i) \
;         __builtin_amdgcn_global_load_lds((const unsigned*)((const char*)(gbase) + (voff)[_i]), (PG8_LAS unsigned*)(lds + (bufoff) + ldsw + _i * 8192), 16, 0, 0); } while (0)
; #define PG8_LDA(dst, b, h) do { _Pragma("unroll") for (int m = 0; m < 4; ++m) _Pragma("unroll") for (int k = 0; k < 2; ++k) dst[m][k] = *(const PG8_LAS bf16x8*)(lds + PG8_SA(b, h) + aoff + m * 2048 + k * 1024); } while (0)
; #define PG8_LDB(dst, b, h) do { _Pragma("unroll") for (int n = 0; n < 2; ++n) _Pragma("unroll") for (int k = 0; k < 2; ++k) dst[n][k] = *(const PG8_LAS bf16x8*)(lds + PG8_SB(b, h) + boff + n * 2048 + k * 1024); } while (0)
; #define PG8_MMA(ai, bj, At, Bt) do { __builtin_amdgcn_s_setprio(1); _Pragma("unroll") for (int m = 0; m < 4; ++m) _Pragma("unroll") for (int n = 0; n < 2; ++n) _Pragma("unroll") for (int k = 0; k < 2; ++k) \
;         acc[ai][bj][m][n] = __builtin_amdgcn_mfma_f32_16x16x32_bf16(Bt[n][k], At[m][k], acc[ai][bj][m][n], 0, 0, 0); __builtin_amdgcn_s_setprio(0); } while (0)
; #define PG8_WAIT_V(n) asm volatile("s_waitcnt vmcnt(" #n ")" ::: "memory")
; #define PG8_WAIT_L(n) asm volatile("s_waitcnt lgkmcnt(" #n ")" ::: "memory")
; #define PG8_BAR __builtin_amdgcn_s_barrier()
; #define PG8_SCHED __builtin_amdgcn_sched_barrier(0)
; template <class Epi, class Sched, bool ALIGN_EPI = false, bool SP2 = false>
; __device__ __forceinline__ void gemm_phase(PG8_LAS unsigned char* lds, const Gemm g, const Sched S, const Epi E) {
;     ...
;             PG8_WAIT_V(8); PG8_WAIT_L(0); PG8_BAR; PG8_MMA(1, 0, At, B0); PG8_MMA(1, 1, At, B1); PG8_BAR; PG8_SCHED;
;             PG8_LDB(B0, 1, 0); PG8_LDB(B1, 1, 1); PG8_SCHED; PG8_LDA(At, 1, 0); PG8_STAGE(PG8_SA(0, 1), a2 + hstep, voffA);
;             PG8_WAIT_V(8); PG8_WAIT_L(0); PG8_BAR; PG8_MMA(0, 0, At, B0); PG8_MMA(0, 1, At, B1); PG8_BAR; PG8_SCHED;
	s_setprio 1
	v_mfma_f32_16x16x32_bf16 v[70:73], v[146:149], v[202:205], v[70:73]
	v_mfma_f32_16x16x32_bf16 v[66:69], v[160:163], v[202:205], v[66:69]
	v_mfma_f32_16x16x32_bf16 v[86:89], v[146:149], v[210:213], v[86:89]
	v_mfma_f32_16x16x32_bf16 v[82:85], v[160:163], v[210:213], v[82:85]
	v_mfma_f32_16x16x32_bf16 v[102:105], v[146:149], v[218:221], v[102:105]
	v_mfma_f32_16x16x32_bf16 v[98:101], v[160:163], v[218:221], v[98:101]
	v_mfma_f32_16x16x32_bf16 v[118:121], v[146:149], v[226:229], v[118:121]
	v_mfma_f32_16x16x32_bf16 v[114:117], v[160:163], v[226:229], v[114:117]
	v_mfma_f32_16x16x32_bf16 v[70:73], v[156:159], v[206:209], v[70:73]
	v_mfma_f32_16x16x32_bf16 v[66:69], v[164:167], v[206:209], v[66:69]
	v_mfma_f32_16x16x32_bf16 v[86:89], v[156:159], v[214:217], v[86:89]
	v_mfma_f32_16x16x32_bf16 v[82:85], v[164:167], v[214:217], v[82:85]
	v_mfma_f32_16x16x32_bf16 v[102:105], v[156:159], v[222:225], v[102:105]
	v_mfma_f32_16x16x32_bf16 v[98:101], v[164:167], v[222:225], v[98:101]
	v_mfma_f32_16x16x32_bf16 v[118:121], v[156:159], v[230:233], v[118:121]
	v_mfma_f32_16x16x32_bf16 v[114:117], v[164:167], v[230:233], v[114:117]
	s_setprio 0
	s_setprio 1
	v_mfma_f32_16x16x32_bf16 v[78:81], v[168:171], v[202:205], v[78:81]
	v_mfma_f32_16x16x32_bf16 v[74:77], v[182:185], v[202:205], v[74:77]
	v_mfma_f32_16x16x32_bf16 v[94:97], v[168:171], v[210:213], v[94:97]
	v_mfma_f32_16x16x32_bf16 v[90:93], v[182:185], v[210:213], v[90:93]
	v_mfma_f32_16x16x32_bf16 v[110:113], v[168:171], v[218:221], v[110:113]
	v_mfma_f32_16x16x32_bf16 v[106:109], v[182:185], v[218:221], v[106:109]
	v_mfma_f32_16x16x32_bf16 v[126:129], v[168:171], v[226:229], v[126:129]
	v_mfma_f32_16x16x32_bf16 v[122:125], v[182:185], v[226:229], v[122:125]
	v_mfma_f32_16x16x32_bf16 v[78:81], v[172:175], v[206:209], v[78:81]
	v_mfma_f32_16x16x32_bf16 v[74:77], v[198:201], v[206:209], v[74:77]
	v_mfma_f32_16x16x32_bf16 v[94:97], v[172:175], v[214:217], v[94:97]
	v_mfma_f32_16x16x32_bf16 v[90:93], v[198:201], v[214:217], v[90:93]
	v_mfma_f32_16x16x32_bf16 v[110:113], v[172:175], v[222:225], v[110:113]
	v_mfma_f32_16x16x32_bf16 v[106:109], v[198:201], v[222:225], v[106:109]
	v_mfma_f32_16x16x32_bf16 v[126:129], v[172:175], v[230:233], v[126:129]
	v_mfma_f32_16x16x32_bf16 v[122:125], v[198:201], v[230:233], v[122:125]
	s_setprio 0
	s_barrier
	v_add_u32_e32 v155, 0x18000, v152
	ds_read_b128 v[146:149], v155
	ds_read_b128 v[156:159], v155 offset:1024
	ds_read_b128 v[160:163], v155 offset:2048
	ds_read_b128 v[164:167], v155 offset:3072
	v_add_u32_e32 v155, 0x1c000, v152
	ds_read_b128 v[168:171], v155
	ds_read_b128 v[172:175], v155 offset:1024
	ds_read_b128 v[182:185], v155 offset:2048
	ds_read_b128 v[198:201], v155 offset:3072
	s_add_i32 s20, 0, 0x18000
	s_add_i32 s21, 0, 0x1c000
	s_add_u32 s14, s18, s28
	s_addc_u32 s15, s19, 0
	s_mov_b32 m0, s74
	v_lshl_add_u64 v[244:245], s[14:15], 0, v[130:131]
	ds_read_b128 v[202:205], v154 offset:32768
	ds_read_b128 v[206:209], v154 offset:33792
	ds_read_b128 v[210:213], v154 offset:34816
	ds_read_b128 v[214:217], v154 offset:35840
	ds_read_b128 v[218:221], v154 offset:36864
	ds_read_b128 v[222:225], v154 offset:37888
	ds_read_b128 v[226:229], v154 offset:38912
	ds_read_b128 v[230:233], v154 offset:39936
	global_load_lds_dwordx4 v[244:245], off
	v_lshl_add_u64 v[244:245], s[14:15], 0, v[132:133]
	s_mov_b32 m0, s75
	s_nop 0
	global_load_lds_dwordx4 v[244:245], off
	s_waitcnt vmcnt(8)
	s_waitcnt lgkmcnt(0)
	s_barrier
	s_setprio 1
	v_mfma_f32_16x16x32_bf16 v[62:65], v[146:149], v[202:205], v[62:65]
	v_mfma_f32_16x16x32_bf16 v[54:57], v[160:163], v[202:205], v[54:57]
	v_mfma_f32_16x16x32_bf16 v[14:17], v[146:149], v[210:213], v[14:17]
	v_mfma_f32_16x16x32_bf16 v[10:13], v[160:163], v[210:213], v[10:13]
	v_mfma_f32_16x16x32_bf16 v[30:33], v[146:149], v[218:221], v[30:33]
	v_mfma_f32_16x16x32_bf16 v[26:29], v[160:163], v[218:221], v[26:29]
	v_mfma_f32_16x16x32_bf16 v[46:49], v[146:149], v[226:229], v[46:49]
	v_mfma_f32_16x16x32_bf16 v[42:45], v[160:163], v[226:229], v[42:45]
	v_mfma_f32_16x16x32_bf16 v[62:65], v[156:159], v[206:209], v[62:65]
	v_mfma_f32_16x16x32_bf16 v[54:57], v[164:167], v[206:209], v[54:57]
	v_mfma_f32_16x16x32_bf16 v[14:17], v[156:159], v[214:217], v[14:17]
	v_mfma_f32_16x16x32_bf16 v[10:13], v[164:167], v[214:217], v[10:13]
	v_mfma_f32_16x16x32_bf16 v[30:33], v[156:159], v[222:225], v[30:33]
	v_mfma_f32_16x16x32_bf16 v[26:29], v[164:167], v[222:225], v[26:29]
	v_mfma_f32_16x16x32_bf16 v[46:49], v[156:159], v[230:233], v[46:49]
	v_mfma_f32_16x16x32_bf16 v[42:45], v[164:167], v[230:233], v[42:45]
	s_setprio 0
	s_setprio 1
	v_mfma_f32_16x16x32_bf16 v[6:9], v[168:171], v[202:205], v[6:9]
	v_mfma_f32_16x16x32_bf16 v[2:5], v[182:185], v[202:205], v[2:5]
	v_mfma_f32_16x16x32_bf16 v[22:25], v[168:171], v[210:213], v[22:25]
	v_mfma_f32_16x16x32_bf16 v[18:21], v[182:185], v[210:213], v[18:21]
	v_mfma_f32_16x16x32_bf16 v[38:41], v[168:171], v[218:221], v[38:41]
	v_mfma_f32_16x16x32_bf16 v[34:37], v[182:185], v[218:221], v[34:37]
	v_mfma_f32_16x16x32_bf16 v[58:61], v[168:171], v[226:229], v[58:61]
	v_mfma_f32_16x16x32_bf16 v[50:53], v[182:185], v[226:229], v[50:53]
	v_mfma_f32_16x16x32_bf16 v[6:9], v[172:175], v[206:209], v[6:9]
	v_mfma_f32_16x16x32_bf16 v[2:5], v[198:201], v[206:209], v[2:5]
	v_mfma_f32_16x16x32_bf16 v[22:25], v[172:175], v[214:217], v[22:25]
	v_mfma_f32_16x16x32_bf16 v[18:21], v[198:201], v[214:217], v[18:21]
	v_mfma_f32_16x16x32_bf16 v[38:41], v[172:175], v[222:225], v[38:41]
	v_mfma_f32_16x16x32_bf16 v[34:37], v[198:201], v[222:225], v[34:37]
	v_mfma_f32_16x16x32_bf16 v[58:61], v[172:175], v[230:233], v[58:61]
	v_mfma_f32_16x16x32_bf16 v[50:53], v[198:201], v[230:233], v[50:53]
	s_setprio 0
	s_barrier
; #define PG8_STAGE(bufoff, gbase, voff) do { _Pragma("unroll") for (int _i = 0; _i < 2; ++_i) \
;         __builtin_amdgcn_global_load_lds((const unsigned*)((const char*)(gbase) + (voff)[_i]), (PG8_LAS unsigned*)(lds + (bufoff) + ldsw + _i * 8192), 16, 0, 0); } while (0)
; #define PG8_LDA(dst, b, h) do { _Pragma("unroll") for (int m = 0; m < 4; ++m) _Pragma("unroll") for (int k = 0; k < 2; ++k) dst[m][k] = *(const PG8_LAS bf16x8*)(lds + PG8_SA(b, h) + aoff + m * 2048 + k * 1024); } while (0)
; #define PG8_MMA(ai, bj, At, Bt) do { __builtin_amdgcn_s_setprio(1); _Pragma("unroll") for (int m = 0; m < 4; ++m) _Pragma("unroll") for (int n = 0; n < 2; ++n) _Pragma("unroll") for (int k = 0; k < 2; ++k) \
;         acc[ai][bj][m][n] = __builtin_amdgcn_mfma_f32_16x16x32_bf16(Bt[n][k], At[m][k], acc[ai][bj][m][n], 0, 0, 0); __builtin_amdgcn_s_setprio(0); } while (0)
; #define PG8_WAIT_V(n) asm volatile("s_waitcnt vmcnt(" #n ")" ::: "memory")
; #define PG8_WAIT_L(n) asm volatile("s_waitcnt lgkmcnt(" #n ")" ::: "memory")
; #define PG8_BAR __builtin_amdgcn_s_barrier()
; #define PG8_SCHED __builtin_amdgcn_sched_barrier(0)
; template <class Epi, class Sched, bool ALIGN_EPI = false, bool SP2 = false>
; __device__ __forceinline__ void gemm_phase(PG8_LAS unsigned char* lds, const Gemm g, const Sched S, const Epi E) {
;     ...
;             PG8_LDA(At, 1, 1); PG8_STAGE(PG8_SB(1, 0), b3, voffB); PG8_STAGE(PG8_SB(1, 1), b3 + hstep, voffB); PG8_STAGE(PG8_SA(1, 0), a3, voffA);
;             PG8_WAIT_V(8); PG8_WAIT_L(0); PG8_BAR; PG8_MMA(1, 0, At, B0); PG8_MMA(1, 1, At, B1); PG8_BAR; PG8_SCHED;
	s_add_i32 s14, s20, s71
	v_lshl_add_u64 v[176:177], v[176:177], 0, s[12:13]
	s_mov_b32 m0, s14
	ds_read_b128 v[202:205], v154 offset:49152
	ds_read_b128 v[206:209], v154 offset:50176
	ds_read_b128 v[210:213], v154 offset:51200
	ds_read_b128 v[214:217], v154 offset:52224
	ds_read_b128 v[218:221], v154 offset:53248
	ds_read_b128 v[222:225], v154 offset:54272
	ds_read_b128 v[226:229], v154 offset:55296
	ds_read_b128 v[230:233], v154 offset:56320
	global_load_lds_dwordx4 v[176:177], off
	v_lshl_add_u64 v[176:177], v[234:235], 0, s[12:13]
	s_add_i32 m0, s14, 0x2000
	s_add_i32 s14, s21, s71
	global_load_lds_dwordx4 v[176:177], off
	v_lshl_add_u64 v[176:177], v[236:237], 0, s[12:13]
	s_mov_b32 m0, s14
	s_nop 0
	global_load_lds_dwordx4 v[176:177], off
	v_lshl_add_u64 v[176:177], v[238:239], 0, s[12:13]
	s_add_i32 m0, s14, 0x2000
	s_nop 0
	global_load_lds_dwordx4 v[176:177], off
	v_lshl_add_u64 v[176:177], v[240:241], 0, s[12:13]
	s_mov_b32 m0, s77
	s_nop 0
	global_load_lds_dwordx4 v[176:177], off
	v_lshl_add_u64 v[176:177], v[242:243], 0, s[12:13]
	s_mov_b32 m0, s78
	s_nop 0
	global_load_lds_dwordx4 v[176:177], off
	s_waitcnt vmcnt(8)
	s_waitcnt lgkmcnt(0)
	s_barrier
	s_setprio 1
	v_mfma_f32_16x16x32_bf16 v[70:73], v[146:149], v[202:205], v[70:73]
	v_mfma_f32_16x16x32_bf16 v[66:69], v[160:163], v[202:205], v[66:69]
	v_mfma_f32_16x16x32_bf16 v[86:89], v[146:149], v[210:213], v[86:89]
	v_mfma_f32_16x16x32_bf16 v[82:85], v[160:163], v[210:213], v[82:85]
	v_mfma_f32_16x16x32_bf16 v[102:105], v[146:149], v[218:221], v[102:105]
	v_mfma_f32_16x16x32_bf16 v[98:101], v[160:163], v[218:221], v[98:101]
	v_mfma_f32_16x16x32_bf16 v[118:121], v[146:149], v[226:229], v[118:121]
	v_mfma_f32_16x16x32_bf16 v[114:117], v[160:163], v[226:229], v[114:117]
	v_mfma_f32_16x16x32_bf16 v[70:73], v[156:159], v[206:209], v[70:73]
	v_mfma_f32_16x16x32_bf16 v[66:69], v[164:167], v[206:209], v[66:69]
	v_mfma_f32_16x16x32_bf16 v[86:89], v[156:159], v[214:217], v[86:89]
	v_mfma_f32_16x16x32_bf16 v[82:85], v[164:167], v[214:217], v[82:85]
	v_mfma_f32_16x16x32_bf16 v[102:105], v[156:159], v[222:225], v[102:105]
	v_mfma_f32_16x16x32_bf16 v[98:101], v[164:167], v[222:225], v[98:101]
	v_mfma_f32_16x16x32_bf16 v[118:121], v[156:159], v[230:233], v[118:121]
	v_mfma_f32_16x16x32_bf16 v[114:117], v[164:167], v[230:233], v[114:117]
	s_setprio 0
	s_setprio 1
	v_mfma_f32_16x16x32_bf16 v[78:81], v[168:171], v[202:205], v[78:81]
	v_mfma_f32_16x16x32_bf16 v[74:77], v[182:185], v[202:205], v[74:77]
	v_mfma_f32_16x16x32_bf16 v[94:97], v[168:171], v[210:213], v[94:97]
	v_mfma_f32_16x16x32_bf16 v[90:93], v[182:185], v[210:213], v[90:93]
	v_mfma_f32_16x16x32_bf16 v[110:113], v[168:171], v[218:221], v[110:113]
	v_mfma_f32_16x16x32_bf16 v[106:109], v[182:185], v[218:221], v[106:109]
	v_mfma_f32_16x16x32_bf16 v[126:129], v[168:171], v[226:229], v[126:129]
	v_mfma_f32_16x16x32_bf16 v[122:125], v[182:185], v[226:229], v[122:125]
	v_mfma_f32_16x16x32_bf16 v[78:81], v[172:175], v[206:209], v[78:81]
	v_mfma_f32_16x16x32_bf16 v[74:77], v[198:201], v[206:209], v[74:77]
	v_mfma_f32_16x16x32_bf16 v[94:97], v[172:175], v[214:217], v[94:97]
	v_mfma_f32_16x16x32_bf16 v[90:93], v[198:201], v[214:217], v[90:93]
	v_mfma_f32_16x16x32_bf16 v[110:113], v[172:175], v[222:225], v[110:113]
	v_mfma_f32_16x16x32_bf16 v[106:109], v[198:201], v[222:225], v[106:109]
	v_mfma_f32_16x16x32_bf16 v[126:129], v[172:175], v[230:233], v[126:129]
	v_mfma_f32_16x16x32_bf16 v[122:125], v[198:201], v[230:233], v[122:125]
	s_setprio 0
	s_add_u32 s16, s16, 0x100
	s_addc_u32 s17, s17, 0
	v_lshl_add_u64 v[144:145], v[144:145], 0, s[88:89]
	v_lshl_add_u64 v[142:143], v[142:143], 0, s[88:89]
	s_cmp_ge_u32 s3, s76
	s_mov_b32 s14, s3
	s_barrier
	s_cbranch_scc0 .LBB0_538
	s_and_b64 vcc, exec, s[62:63]
	s_cbranch_vccz .LBB0_541
	s_barrier
